# v067 with the two LDS-DMA loads of each load segment issued before the fragment ds_reads instead of after
# baseline (speedup 1.0000x reference)
.LBB0_134:
	s_add_u32 s28, s66, 0xfffc0080
	s_addc_u32 s29, s67, -1
	s_add_i32 s88, 0, 0x10000
	s_cmp_eq_u32 vcc_lo, 12
	s_cselect_b32 s71, s5, s29
	s_cselect_b32 s70, s7, s28
	s_cselect_b32 s69, s17, s91
	s_cselect_b32 s68, s19, s85
	s_add_i32 m0, s73, 0xc000
	s_nop 0
	global_load_lds_dwordx4 v144, s[66:67]
	s_add_i32 m0, s73, 0xe000
	s_nop 0
	global_load_lds_dwordx4 v146, s[66:67]
	ds_read_b128 v[128:131], v172
	ds_read_b128 v[132:135], v172 offset:1024
	ds_read_b128 v[148:151], v172 offset:2048
	ds_read_b128 v[152:155], v172 offset:3072
	ds_read_b128 v[156:159], v192
	ds_read_b128 v[164:167], v192 offset:2048
	ds_read_b128 v[194:197], v192 offset:4096
	ds_read_b128 v[202:205], v192 offset:6144
	ds_read_b128 v[160:163], v192 offset:1024
	ds_read_b128 v[168:171], v192 offset:3072
	ds_read_b128 v[198:201], v192 offset:5120
	ds_read_b128 v[206:209], v192 offset:7168
	s_waitcnt lgkmcnt(8)
	s_barrier
	s_waitcnt lgkmcnt(7)
	v_mfma_f32_16x16x32_bf16 v[124:127], v[128:131], v[156:159], v[124:127]
	v_mfma_f32_16x16x32_bf16 v[120:123], v[148:151], v[156:159], v[120:123]
	s_waitcnt lgkmcnt(6)
	v_mfma_f32_16x16x32_bf16 v[108:111], v[128:131], v[164:167], v[108:111]
	v_mfma_f32_16x16x32_bf16 v[104:107], v[148:151], v[164:167], v[104:107]
	s_waitcnt lgkmcnt(5)
	v_mfma_f32_16x16x32_bf16 v[92:95], v[128:131], v[194:197], v[92:95]
	v_mfma_f32_16x16x32_bf16 v[88:91], v[148:151], v[194:197], v[88:91]
	s_waitcnt lgkmcnt(4)
	v_mfma_f32_16x16x32_bf16 v[76:79], v[128:131], v[202:205], v[76:79]
	v_mfma_f32_16x16x32_bf16 v[72:75], v[148:151], v[202:205], v[72:75]
	s_waitcnt lgkmcnt(3)
	v_mfma_f32_16x16x32_bf16 v[124:127], v[132:135], v[160:163], v[124:127]
	v_mfma_f32_16x16x32_bf16 v[120:123], v[152:155], v[160:163], v[120:123]
	s_waitcnt lgkmcnt(2)
	v_mfma_f32_16x16x32_bf16 v[108:111], v[132:135], v[168:171], v[108:111]
	v_mfma_f32_16x16x32_bf16 v[104:107], v[152:155], v[168:171], v[104:107]
	s_waitcnt lgkmcnt(1)
	v_mfma_f32_16x16x32_bf16 v[92:95], v[132:135], v[198:201], v[92:95]
	v_mfma_f32_16x16x32_bf16 v[88:91], v[152:155], v[198:201], v[88:91]
	s_waitcnt lgkmcnt(0)
	v_mfma_f32_16x16x32_bf16 v[76:79], v[132:135], v[206:209], v[76:79]
	v_mfma_f32_16x16x32_bf16 v[72:75], v[152:155], v[206:209], v[72:75]
	s_barrier
	s_add_i32 s89, 0, 0x14000
	s_add_i32 s28, s88, s72
	s_mov_b32 m0, s28
	s_nop 0
	global_load_lds_dwordx4 v138, s[68:69]
	s_add_i32 m0, s28, 0x2000
	s_nop 0
	global_load_lds_dwordx4 v142, s[68:69]
	ds_read_b128 v[210:213], v172 offset:16384
	ds_read_b128 v[214:217], v172 offset:17408
	ds_read_b128 v[232:235], v172 offset:18432
	ds_read_b128 v[236:239], v172 offset:19456
	s_barrier
	s_waitcnt lgkmcnt(3)
	v_mfma_f32_16x16x32_bf16 v[116:119], v[210:213], v[156:159], v[116:119]
	s_waitcnt lgkmcnt(1)
	v_mfma_f32_16x16x32_bf16 v[112:115], v[232:235], v[156:159], v[112:115]
	v_mfma_f32_16x16x32_bf16 v[100:103], v[210:213], v[164:167], v[100:103]
	v_mfma_f32_16x16x32_bf16 v[96:99], v[232:235], v[164:167], v[96:99]
	v_mfma_f32_16x16x32_bf16 v[84:87], v[210:213], v[194:197], v[84:87]
	v_mfma_f32_16x16x32_bf16 v[80:83], v[232:235], v[194:197], v[80:83]
	v_mfma_f32_16x16x32_bf16 v[68:71], v[210:213], v[202:205], v[68:71]
	v_mfma_f32_16x16x32_bf16 v[64:67], v[232:235], v[202:205], v[64:67]
	v_mfma_f32_16x16x32_bf16 v[116:119], v[214:217], v[160:163], v[116:119]
	s_waitcnt lgkmcnt(0)
	v_mfma_f32_16x16x32_bf16 v[112:115], v[236:239], v[160:163], v[112:115]
	v_mfma_f32_16x16x32_bf16 v[100:103], v[214:217], v[168:171], v[100:103]
	v_mfma_f32_16x16x32_bf16 v[96:99], v[236:239], v[168:171], v[96:99]
	v_mfma_f32_16x16x32_bf16 v[84:87], v[214:217], v[198:201], v[84:87]
	v_mfma_f32_16x16x32_bf16 v[80:83], v[236:239], v[198:201], v[80:83]
	v_mfma_f32_16x16x32_bf16 v[68:71], v[214:217], v[206:209], v[68:71]
	v_mfma_f32_16x16x32_bf16 v[64:67], v[236:239], v[206:209], v[64:67]
	s_mov_b32 m0, s73
	s_barrier
	global_load_lds_dwordx4 v136, s[70:71]
	s_mov_b32 m0, s74
	s_nop 0
	global_load_lds_dwordx4 v140, s[70:71]
	ds_read_b128 v[156:159], v192 offset:16384
	ds_read_b128 v[164:167], v192 offset:18432
	ds_read_b128 v[194:197], v192 offset:20480
	ds_read_b128 v[202:205], v192 offset:22528
	ds_read_b128 v[160:163], v192 offset:17408
	ds_read_b128 v[168:171], v192 offset:19456
	ds_read_b128 v[198:201], v192 offset:21504
	ds_read_b128 v[206:209], v192 offset:23552
	s_barrier
	s_waitcnt lgkmcnt(7)
	v_mfma_f32_16x16x32_bf16 v[60:63], v[128:131], v[156:159], v[60:63]
	v_mfma_f32_16x16x32_bf16 v[56:59], v[148:151], v[156:159], v[56:59]
	s_waitcnt lgkmcnt(6)
	v_mfma_f32_16x16x32_bf16 v[44:47], v[128:131], v[164:167], v[44:47]
	v_mfma_f32_16x16x32_bf16 v[40:43], v[148:151], v[164:167], v[40:43]
	s_waitcnt lgkmcnt(5)
	v_mfma_f32_16x16x32_bf16 v[28:31], v[128:131], v[194:197], v[28:31]
	v_mfma_f32_16x16x32_bf16 v[24:27], v[148:151], v[194:197], v[24:27]
	s_waitcnt lgkmcnt(4)
	v_mfma_f32_16x16x32_bf16 v[12:15], v[128:131], v[202:205], v[12:15]
	v_mfma_f32_16x16x32_bf16 v[8:11], v[148:151], v[202:205], v[8:11]
	s_waitcnt lgkmcnt(3)
	v_mfma_f32_16x16x32_bf16 v[60:63], v[132:135], v[160:163], v[60:63]
	v_mfma_f32_16x16x32_bf16 v[56:59], v[152:155], v[160:163], v[56:59]
	s_waitcnt lgkmcnt(2)
	v_mfma_f32_16x16x32_bf16 v[44:47], v[132:135], v[168:171], v[44:47]
	v_mfma_f32_16x16x32_bf16 v[40:43], v[152:155], v[168:171], v[40:43]
	s_waitcnt lgkmcnt(1)
	v_mfma_f32_16x16x32_bf16 v[28:31], v[132:135], v[198:201], v[28:31]
	v_mfma_f32_16x16x32_bf16 v[24:27], v[152:155], v[198:201], v[24:27]
	s_waitcnt lgkmcnt(0)
	v_mfma_f32_16x16x32_bf16 v[12:15], v[132:135], v[206:209], v[12:15]
	v_mfma_f32_16x16x32_bf16 v[8:11], v[152:155], v[206:209], v[8:11]
	s_barrier
	s_add_u32 s28, s68, 0x40000
	s_addc_u32 s29, s69, 0
	s_add_i32 s88, s89, s72
	s_mov_b32 m0, s88
	s_nop 0
	global_load_lds_dwordx4 v138, s[28:29]
	s_add_i32 m0, s88, 0x2000
	s_nop 0
	global_load_lds_dwordx4 v142, s[28:29]
	s_waitcnt vmcnt(6)
	s_barrier
	v_mfma_f32_16x16x32_bf16 v[52:55], v[210:213], v[156:159], v[52:55]
	v_mfma_f32_16x16x32_bf16 v[48:51], v[232:235], v[156:159], v[48:51]
	v_mfma_f32_16x16x32_bf16 v[36:39], v[210:213], v[164:167], v[36:39]
	v_mfma_f32_16x16x32_bf16 v[32:35], v[232:235], v[164:167], v[32:35]
	v_mfma_f32_16x16x32_bf16 v[20:23], v[210:213], v[194:197], v[20:23]
	v_mfma_f32_16x16x32_bf16 v[16:19], v[232:235], v[194:197], v[16:19]
	v_mfma_f32_16x16x32_bf16 v[4:7], v[210:213], v[202:205], v[4:7]
	v_mfma_f32_16x16x32_bf16 v[0:3], v[232:235], v[202:205], v[0:3]
	v_mfma_f32_16x16x32_bf16 v[52:55], v[214:217], v[160:163], v[52:55]
	v_mfma_f32_16x16x32_bf16 v[48:51], v[236:239], v[160:163], v[48:51]
	v_mfma_f32_16x16x32_bf16 v[36:39], v[214:217], v[168:171], v[36:39]
	v_mfma_f32_16x16x32_bf16 v[32:35], v[236:239], v[168:171], v[32:35]
	v_mfma_f32_16x16x32_bf16 v[20:23], v[214:217], v[198:201], v[20:23]
	v_mfma_f32_16x16x32_bf16 v[16:19], v[236:239], v[198:201], v[16:19]
	v_mfma_f32_16x16x32_bf16 v[4:7], v[214:217], v[206:209], v[4:7]
	v_mfma_f32_16x16x32_bf16 v[0:3], v[236:239], v[206:209], v[0:3]
	s_add_i32 s88, 0, 0x18000
	s_barrier
	s_add_u32 s28, s70, 0x40000
	s_addc_u32 s29, s71, 0
	s_mov_b32 m0, s75
	s_nop 0
	global_load_lds_dwordx4 v136, s[28:29]
	s_mov_b32 m0, s76
	s_nop 0
	global_load_lds_dwordx4 v140, s[28:29]
	ds_read_b128 v[128:131], v172 offset:32768
	ds_read_b128 v[132:135], v172 offset:33792
	ds_read_b128 v[148:151], v172 offset:34816
	ds_read_b128 v[152:155], v172 offset:35840
	ds_read_b128 v[156:159], v192 offset:32768
	ds_read_b128 v[164:167], v192 offset:34816
	ds_read_b128 v[194:197], v192 offset:36864
	ds_read_b128 v[202:205], v192 offset:38912
	ds_read_b128 v[160:163], v192 offset:33792
	ds_read_b128 v[168:171], v192 offset:35840
	ds_read_b128 v[198:201], v192 offset:37888
	ds_read_b128 v[206:209], v192 offset:39936
	s_waitcnt lgkmcnt(8)
	s_barrier
	s_waitcnt lgkmcnt(7)
	v_mfma_f32_16x16x32_bf16 v[124:127], v[128:131], v[156:159], v[124:127]
	v_mfma_f32_16x16x32_bf16 v[120:123], v[148:151], v[156:159], v[120:123]
	s_waitcnt lgkmcnt(6)
	v_mfma_f32_16x16x32_bf16 v[108:111], v[128:131], v[164:167], v[108:111]
	v_mfma_f32_16x16x32_bf16 v[104:107], v[148:151], v[164:167], v[104:107]
	s_waitcnt lgkmcnt(5)
	v_mfma_f32_16x16x32_bf16 v[92:95], v[128:131], v[194:197], v[92:95]
	v_mfma_f32_16x16x32_bf16 v[88:91], v[148:151], v[194:197], v[88:91]
	s_waitcnt lgkmcnt(4)
	v_mfma_f32_16x16x32_bf16 v[76:79], v[128:131], v[202:205], v[76:79]
	v_mfma_f32_16x16x32_bf16 v[72:75], v[148:151], v[202:205], v[72:75]
	s_waitcnt lgkmcnt(3)
	v_mfma_f32_16x16x32_bf16 v[124:127], v[132:135], v[160:163], v[124:127]
	v_mfma_f32_16x16x32_bf16 v[120:123], v[152:155], v[160:163], v[120:123]
	s_waitcnt lgkmcnt(2)
	v_mfma_f32_16x16x32_bf16 v[108:111], v[132:135], v[168:171], v[108:111]
	v_mfma_f32_16x16x32_bf16 v[104:107], v[152:155], v[168:171], v[104:107]
	s_waitcnt lgkmcnt(1)
	v_mfma_f32_16x16x32_bf16 v[92:95], v[132:135], v[198:201], v[92:95]
	v_mfma_f32_16x16x32_bf16 v[88:91], v[152:155], v[198:201], v[88:91]
	s_waitcnt lgkmcnt(0)
	v_mfma_f32_16x16x32_bf16 v[76:79], v[132:135], v[206:209], v[76:79]
	v_mfma_f32_16x16x32_bf16 v[72:75], v[152:155], v[206:209], v[72:75]
	s_barrier
	s_add_i32 s98, 0, 0x1c000
	s_add_i32 s28, s88, s72
	s_add_i32 m0, s28, 0xffffff80
	s_nop 0
	global_load_lds_dwordx4 v138, s[68:69] offset:128
	s_add_i32 m0, s28, 0x1f80
	s_nop 0
	global_load_lds_dwordx4 v142, s[68:69] offset:128
	ds_read_b128 v[210:213], v172 offset:49152
	ds_read_b128 v[214:217], v172 offset:50176
	ds_read_b128 v[232:235], v172 offset:51200
	ds_read_b128 v[236:239], v172 offset:52224
	s_barrier
	s_waitcnt lgkmcnt(3)
	v_mfma_f32_16x16x32_bf16 v[116:119], v[210:213], v[156:159], v[116:119]
	s_waitcnt lgkmcnt(1)
	v_mfma_f32_16x16x32_bf16 v[112:115], v[232:235], v[156:159], v[112:115]
	v_mfma_f32_16x16x32_bf16 v[100:103], v[210:213], v[164:167], v[100:103]
	v_mfma_f32_16x16x32_bf16 v[96:99], v[232:235], v[164:167], v[96:99]
	v_mfma_f32_16x16x32_bf16 v[84:87], v[210:213], v[194:197], v[84:87]
	v_mfma_f32_16x16x32_bf16 v[80:83], v[232:235], v[194:197], v[80:83]
	v_mfma_f32_16x16x32_bf16 v[68:71], v[210:213], v[202:205], v[68:71]
	v_mfma_f32_16x16x32_bf16 v[64:67], v[232:235], v[202:205], v[64:67]
	v_mfma_f32_16x16x32_bf16 v[116:119], v[214:217], v[160:163], v[116:119]
	s_waitcnt lgkmcnt(0)
	v_mfma_f32_16x16x32_bf16 v[112:115], v[236:239], v[160:163], v[112:115]
	v_mfma_f32_16x16x32_bf16 v[100:103], v[214:217], v[168:171], v[100:103]
	v_mfma_f32_16x16x32_bf16 v[96:99], v[236:239], v[168:171], v[96:99]
	v_mfma_f32_16x16x32_bf16 v[84:87], v[214:217], v[198:201], v[84:87]
	v_mfma_f32_16x16x32_bf16 v[80:83], v[236:239], v[198:201], v[80:83]
	v_mfma_f32_16x16x32_bf16 v[68:71], v[214:217], v[206:209], v[68:71]
	v_mfma_f32_16x16x32_bf16 v[64:67], v[236:239], v[206:209], v[64:67]
	s_add_i32 m0, s79, 0xffffff80
	s_barrier
	global_load_lds_dwordx4 v136, s[70:71] offset:128
	s_add_i32 m0, s80, 0xffffff80
	s_nop 0
	global_load_lds_dwordx4 v140, s[70:71] offset:128
	ds_read_b128 v[156:159], v192 offset:49152
	ds_read_b128 v[164:167], v192 offset:51200
	ds_read_b128 v[194:197], v192 offset:53248
	ds_read_b128 v[202:205], v192 offset:55296
	ds_read_b128 v[160:163], v192 offset:50176
	ds_read_b128 v[168:171], v192 offset:52224
	ds_read_b128 v[198:201], v192 offset:54272
	ds_read_b128 v[206:209], v192 offset:56320
	s_barrier
	s_waitcnt lgkmcnt(7)
	v_mfma_f32_16x16x32_bf16 v[60:63], v[128:131], v[156:159], v[60:63]
	v_mfma_f32_16x16x32_bf16 v[56:59], v[148:151], v[156:159], v[56:59]
	s_waitcnt lgkmcnt(6)
	v_mfma_f32_16x16x32_bf16 v[44:47], v[128:131], v[164:167], v[44:47]
	v_mfma_f32_16x16x32_bf16 v[40:43], v[148:151], v[164:167], v[40:43]
	s_waitcnt lgkmcnt(5)
	v_mfma_f32_16x16x32_bf16 v[28:31], v[128:131], v[194:197], v[28:31]
	v_mfma_f32_16x16x32_bf16 v[24:27], v[148:151], v[194:197], v[24:27]
	s_waitcnt lgkmcnt(4)
	v_mfma_f32_16x16x32_bf16 v[12:15], v[128:131], v[202:205], v[12:15]
	v_mfma_f32_16x16x32_bf16 v[8:11], v[148:151], v[202:205], v[8:11]
	s_waitcnt lgkmcnt(3)
	v_mfma_f32_16x16x32_bf16 v[60:63], v[132:135], v[160:163], v[60:63]
	v_mfma_f32_16x16x32_bf16 v[56:59], v[152:155], v[160:163], v[56:59]
	s_waitcnt lgkmcnt(2)
	v_mfma_f32_16x16x32_bf16 v[44:47], v[132:135], v[168:171], v[44:47]
	v_mfma_f32_16x16x32_bf16 v[40:43], v[152:155], v[168:171], v[40:43]
	s_waitcnt lgkmcnt(1)
	v_mfma_f32_16x16x32_bf16 v[28:31], v[132:135], v[198:201], v[28:31]
	v_mfma_f32_16x16x32_bf16 v[24:27], v[152:155], v[198:201], v[24:27]
	s_waitcnt lgkmcnt(0)
	v_mfma_f32_16x16x32_bf16 v[12:15], v[132:135], v[206:209], v[12:15]
	v_mfma_f32_16x16x32_bf16 v[8:11], v[152:155], v[206:209], v[8:11]
	s_barrier
	s_add_u32 s28, s68, 0x40080
	s_addc_u32 s29, s69, 0
	s_add_i32 s68, s98, s72
	s_mov_b32 m0, s68
	s_nop 0
	global_load_lds_dwordx4 v138, s[28:29]
	s_add_i32 m0, s68, 0x2000
	s_nop 0
	global_load_lds_dwordx4 v142, s[28:29]
	s_waitcnt vmcnt(6)
	s_barrier
	v_mfma_f32_16x16x32_bf16 v[52:55], v[210:213], v[156:159], v[52:55]
	v_mfma_f32_16x16x32_bf16 v[48:51], v[232:235], v[156:159], v[48:51]
	v_mfma_f32_16x16x32_bf16 v[36:39], v[210:213], v[164:167], v[36:39]
	v_mfma_f32_16x16x32_bf16 v[32:35], v[232:235], v[164:167], v[32:35]
	v_mfma_f32_16x16x32_bf16 v[20:23], v[210:213], v[194:197], v[20:23]
	v_mfma_f32_16x16x32_bf16 v[16:19], v[232:235], v[194:197], v[16:19]
	v_mfma_f32_16x16x32_bf16 v[4:7], v[210:213], v[202:205], v[4:7]
	v_mfma_f32_16x16x32_bf16 v[0:3], v[232:235], v[202:205], v[0:3]
	v_mfma_f32_16x16x32_bf16 v[52:55], v[214:217], v[160:163], v[52:55]
	v_mfma_f32_16x16x32_bf16 v[48:51], v[236:239], v[160:163], v[48:51]
	v_mfma_f32_16x16x32_bf16 v[36:39], v[214:217], v[168:171], v[36:39]
	v_mfma_f32_16x16x32_bf16 v[32:35], v[236:239], v[168:171], v[32:35]
	v_mfma_f32_16x16x32_bf16 v[20:23], v[214:217], v[198:201], v[20:23]
	v_mfma_f32_16x16x32_bf16 v[16:19], v[236:239], v[198:201], v[16:19]
	v_mfma_f32_16x16x32_bf16 v[4:7], v[214:217], v[206:209], v[4:7]
	v_mfma_f32_16x16x32_bf16 v[0:3], v[236:239], v[206:209], v[0:3]
	s_add_i32 vcc_lo, vcc_lo, 2
	s_add_u32 s66, s66, 0x100
	s_addc_u32 s67, s67, 0
	s_add_u32 s85, s85, 0x100
	s_addc_u32 s91, s91, 0
	s_cmp_lt_u32 vcc_lo, 14
	s_barrier
	s_cbranch_scc1 .LBB0_134
	s_lshl_b32 s4, s4, 8
	v_mov_b32_e32 v176, v175
	v_mov_b32_e32 v188, v190
	s_add_i32 s4, s4, s77
	s_cmp_gt_i32 s6, 7
	v_add_u32_e32 v148, s4, v176
	v_lshlrev_b32_e32 v128, 2, v188
	v_ashrrev_i32_e32 v129, 31, v128
	v_ashrrev_i32_e32 v149, 31, v148
	v_lshl_add_u64 v[128:129], v[128:129], 2, s[8:9]
	v_lshlrev_b64 v[130:131], 6, v[148:149]
	v_add_u32_e32 v166, 16, v148
	v_lshl_add_u64 v[130:131], v[128:129], 0, v[130:131]
	v_ashrrev_i32_e32 v167, 31, v166
	global_load_dwordx4 v[160:163], v[130:131], off
	v_lshlrev_b64 v[130:131], 6, v[166:167]
	v_lshl_add_u64 v[130:131], v[128:129], 0, v[130:131]
	global_load_dwordx4 v[168:171], v[130:131], off
	v_add_u32_e32 v164, 32, v148
	v_ashrrev_i32_e32 v165, 31, v164
	v_lshlrev_b64 v[130:131], 6, v[164:165]
	v_add_u32_e32 v158, 48, v148
	v_lshl_add_u64 v[130:131], v[128:129], 0, v[130:131]
	v_ashrrev_i32_e32 v159, 31, v158
	global_load_dwordx4 v[194:197], v[130:131], off
	v_lshlrev_b64 v[130:131], 6, v[158:159]
	v_lshl_add_u64 v[130:131], v[128:129], 0, v[130:131]
	global_load_dwordx4 v[198:201], v[130:131], off
	v_add_u32_e32 v156, 0x80, v148
	v_ashrrev_i32_e32 v157, 31, v156
	v_lshlrev_b64 v[130:131], 6, v[156:157]
	v_add_u32_e32 v154, 0x90, v148
	v_lshl_add_u64 v[130:131], v[128:129], 0, v[130:131]
	v_ashrrev_i32_e32 v155, 31, v154
	global_load_dwordx4 v[202:205], v[130:131], off
	v_lshlrev_b64 v[130:131], 6, v[154:155]
	v_add_u32_e32 v152, 0xa0, v148
	v_lshl_add_u64 v[130:131], v[128:129], 0, v[130:131]
	v_ashrrev_i32_e32 v153, 31, v152
	global_load_dwordx4 v[206:209], v[130:131], off
	v_lshlrev_b64 v[130:131], 6, v[152:153]
	v_add_u32_e32 v150, 0xb0, v148
	v_lshl_add_u64 v[130:131], v[128:129], 0, v[130:131]
	v_ashrrev_i32_e32 v151, 31, v150
	global_load_dwordx4 v[132:135], v[130:131], off
	v_lshlrev_b64 v[130:131], 6, v[150:151]
	v_lshl_add_u64 v[128:129], v[128:129], 0, v[130:131]
	global_load_dwordx4 v[128:131], v[128:129], off
	s_cselect_b64 s[66:67], -1, 0
	s_lshl_b32 s7, s6, 8
	s_add_i32 s7, s81, s7
	s_cmp_lt_i32 s6, 8
	s_mov_b64 s[68:69], -1
	s_waitcnt vmcnt(0)
	v_mov_b32_e32 v172, v161
	v_mov_b32_e32 v173, v162
	v_mov_b32_e32 v161, v163
	v_mov_b32_e32 v162, v169
	v_mov_b32_e32 v163, v170
	v_mov_b32_e32 v169, v171
	v_pk_add_f32 v[160:161], v[172:173], v[160:161]
	v_pk_add_f32 v[162:163], v[162:163], v[168:169]
	v_mov_b32_e32 v169, v160
	v_mov_b32_e32 v168, v162
	v_mov_b32_e32 v160, v163
	v_pk_add_f32 v[160:161], v[168:169], v[160:161]
	ds_bpermute_b32 v163, v219, v161
	ds_bpermute_b32 v162, v219, v160
	s_waitcnt lgkmcnt(0)
	v_pk_add_f32 v[160:161], v[160:161], v[162:163]
	ds_bpermute_b32 v163, v218, v161
	ds_bpermute_b32 v162, v218, v160
	s_waitcnt lgkmcnt(0)
	v_pk_add_f32 v[160:161], v[160:161], v[162:163]
	s_nop 0
	v_pk_fma_f32 v[172:173], v[160:161], s[30:31], v[178:179] op_sel_hi:[1,0,0]
	v_mov_b32_e32 v162, v199
	v_mul_f32_e32 v160, 0x4b800000, v173
	v_cmp_gt_f32_e32 vcc, s86, v173
	v_mov_b32_e32 v163, v200
	v_mov_b32_e32 v199, v201
	v_cndmask_b32_e32 v160, v173, v160, vcc
	v_rsq_f32_e32 v160, v160
	v_pk_add_f32 v[162:163], v[162:163], v[198:199]
	v_cmp_gt_f32_e64 s[4:5], s86, v172
	v_mov_b32_e32 v168, v162
	v_mul_f32_e32 v161, 0x45800000, v160
	v_cndmask_b32_e32 v174, v160, v161, vcc
	v_mov_b32_e32 v160, v195
	v_mov_b32_e32 v161, v196
	v_mov_b32_e32 v195, v197
	v_pk_add_f32 v[160:161], v[160:161], v[194:195]
	s_nop 0
	v_mov_b32_e32 v169, v160
	v_mov_b32_e32 v160, v163
	v_pk_add_f32 v[160:161], v[168:169], v[160:161]
	ds_bpermute_b32 v163, v219, v161
	ds_bpermute_b32 v162, v219, v160
	s_waitcnt lgkmcnt(0)
	v_pk_add_f32 v[168:169], v[160:161], v[162:163]
	v_mov_b32_e32 v160, v203
	v_mov_b32_e32 v161, v204
	v_mov_b32_e32 v203, v205
	v_mov_b32_e32 v162, v207
	v_mov_b32_e32 v163, v208
	v_mov_b32_e32 v207, v209
	v_pk_add_f32 v[160:161], v[160:161], v[202:203]
	v_pk_add_f32 v[162:163], v[162:163], v[206:207]
	v_mov_b32_e32 v195, v160
	v_mov_b32_e32 v194, v162
	v_mov_b32_e32 v160, v163
	v_pk_add_f32 v[160:161], v[194:195], v[160:161]
	v_mov_b32_e32 v194, v133
	v_mov_b32_e32 v195, v134
	v_mov_b32_e32 v133, v135
	v_mov_b32_e32 v134, v129
	v_mov_b32_e32 v135, v130
	v_mov_b32_e32 v129, v131
	v_pk_add_f32 v[132:133], v[194:195], v[132:133]
	v_pk_add_f32 v[128:129], v[134:135], v[128:129]
	v_mov_b32_e32 v131, v132
	v_mov_b32_e32 v130, v128
	v_mov_b32_e32 v132, v129
	v_pk_add_f32 v[128:129], v[130:131], v[132:133]
	ds_bpermute_b32 v163, v219, v161
	ds_bpermute_b32 v162, v219, v160
	ds_bpermute_b32 v131, v219, v129
	ds_bpermute_b32 v130, v219, v128
	ds_bpermute_b32 v171, v218, v169
	ds_bpermute_b32 v170, v218, v168
	s_waitcnt lgkmcnt(4)
	v_pk_add_f32 v[160:161], v[160:161], v[162:163]
	ds_bpermute_b32 v163, v218, v161
	s_waitcnt lgkmcnt(3)
	v_pk_add_f32 v[132:133], v[128:129], v[130:131]
	ds_bpermute_b32 v162, v218, v160
	ds_bpermute_b32 v135, v218, v133
	ds_bpermute_b32 v134, v218, v132
	v_lshlrev_b32_e32 v128, 3, v188
	v_add_u32_e32 v130, s7, v128
	v_lshlrev_b64 v[188:189], 11, v[148:149]
	v_ashrrev_i32_e32 v131, 31, v130
	s_cbranch_scc1 .LBB0_137
	v_mul_f32_e32 v196, v120, v174
	v_mul_f32_e32 v197, v121, v174
	v_mul_f32_e32 v198, v122, v174
	v_mul_f32_e32 v199, v123, v174
	v_mul_f32_e32 v129, v124, v174
	v_mul_f32_e32 v149, v125, v174
	v_mul_f32_e32 v173, v126, v174
	v_mul_f32_e32 v193, v127, v174
	v_cvt_pk_bf16_f32 v194, v129, v149
	v_cvt_pk_bf16_f32 v195, v173, v193
	v_cvt_pk_bf16_f32 v196, v196, v197
	v_cvt_pk_bf16_f32 v197, v198, v199
	v_lshl_add_u64 v[198:199], s[12:13], 0, v[188:189]
	v_lshl_add_u64 v[198:199], v[130:131], 1, v[198:199]
	global_store_dwordx4 v[198:199], v[194:197], off
	s_mov_b64 s[68:69], 0
	v_mul_f32_e32 v129, v116, v174
	v_mul_f32_e32 v196, v112, v174
	v_mul_f32_e32 v197, v113, v174
	v_mul_f32_e32 v149, v117, v174
	v_mul_f32_e32 v173, v118, v174
	v_mul_f32_e32 v193, v119, v174
	v_mul_f32_e32 v200, v114, v174
	v_mul_f32_e32 v201, v115, v174
	v_cvt_pk_bf16_f32 v194, v129, v149
	v_cvt_pk_bf16_f32 v195, v173, v193
	v_cvt_pk_bf16_f32 v196, v196, v197
	v_cvt_pk_bf16_f32 v197, v200, v201
	global_store_dwordx4 v[198:199], v[194:197], off offset:256

.LBB0_413:
	s_add_i32 vcc_lo, s62, 2
	s_add_u32 s4, s18, 0x100
	s_addc_u32 s5, s19, 0
	s_add_i32 s28, 0, 0x10000
	s_cmp_eq_u32 s13, s62
	s_cselect_b32 s62, s6, s85
	s_cselect_b32 s65, s17, s5
	s_cselect_b32 s64, s16, s4
	s_cselect_b32 s63, s7, s91
	s_add_i32 m0, s69, 0xc000
	s_nop 0
	global_load_lds_dwordx4 v150, s[18:19]
	s_add_i32 m0, s69, 0xe000
	s_nop 0
	global_load_lds_dwordx4 v152, s[18:19]
	ds_read_b128 v[128:131], v174
	ds_read_b128 v[132:135], v174 offset:1024
	ds_read_b128 v[136:139], v174 offset:2048
	ds_read_b128 v[140:143], v174 offset:3072
	ds_read_b128 v[154:157], v165
	ds_read_b128 v[166:169], v165 offset:2048
	ds_read_b128 v[188:191], v165 offset:4096
	ds_read_b128 v[196:199], v165 offset:6144
	ds_read_b128 v[158:161], v165 offset:1024
	ds_read_b128 v[170:173], v165 offset:3072
	ds_read_b128 v[192:195], v165 offset:5120
	ds_read_b128 v[200:203], v165 offset:7168
	s_waitcnt lgkmcnt(8)
	s_barrier
	s_waitcnt lgkmcnt(7)
	v_mfma_f32_16x16x32_bf16 v[124:127], v[128:131], v[154:157], v[124:127]
	v_mfma_f32_16x16x32_bf16 v[120:123], v[136:139], v[154:157], v[120:123]
	s_waitcnt lgkmcnt(6)
	v_mfma_f32_16x16x32_bf16 v[108:111], v[128:131], v[166:169], v[108:111]
	v_mfma_f32_16x16x32_bf16 v[104:107], v[136:139], v[166:169], v[104:107]
	s_waitcnt lgkmcnt(5)
	v_mfma_f32_16x16x32_bf16 v[92:95], v[128:131], v[188:191], v[92:95]
	v_mfma_f32_16x16x32_bf16 v[88:91], v[136:139], v[188:191], v[88:91]
	s_waitcnt lgkmcnt(4)
	v_mfma_f32_16x16x32_bf16 v[76:79], v[128:131], v[196:199], v[76:79]
	v_mfma_f32_16x16x32_bf16 v[72:75], v[136:139], v[196:199], v[72:75]
	s_waitcnt lgkmcnt(3)
	v_mfma_f32_16x16x32_bf16 v[124:127], v[132:135], v[158:161], v[124:127]
	v_mfma_f32_16x16x32_bf16 v[120:123], v[140:143], v[158:161], v[120:123]
	s_waitcnt lgkmcnt(2)
	v_mfma_f32_16x16x32_bf16 v[108:111], v[132:135], v[170:173], v[108:111]
	v_mfma_f32_16x16x32_bf16 v[104:107], v[140:143], v[170:173], v[104:107]
	s_waitcnt lgkmcnt(1)
	v_mfma_f32_16x16x32_bf16 v[92:95], v[132:135], v[192:195], v[92:95]
	v_mfma_f32_16x16x32_bf16 v[88:91], v[140:143], v[192:195], v[88:91]
	s_waitcnt lgkmcnt(0)
	v_mfma_f32_16x16x32_bf16 v[76:79], v[132:135], v[200:203], v[76:79]
	v_mfma_f32_16x16x32_bf16 v[72:75], v[140:143], v[200:203], v[72:75]
	s_barrier
	s_add_i32 s29, 0, 0x14000
	s_add_i32 s18, s28, s68
	s_mov_b32 m0, s18
	s_nop 0
	global_load_lds_dwordx4 v176, s[62:63]
	s_add_i32 m0, s18, 0x2000
	s_nop 0
	global_load_lds_dwordx4 v148, s[62:63]
	ds_read_b128 v[204:207], v174 offset:16384
	ds_read_b128 v[208:211], v174 offset:17408
	ds_read_b128 v[212:215], v174 offset:18432
	ds_read_b128 v[232:235], v174 offset:19456
	s_barrier
	s_waitcnt lgkmcnt(3)
	v_mfma_f32_16x16x32_bf16 v[116:119], v[204:207], v[154:157], v[116:119]
	s_waitcnt lgkmcnt(1)
	v_mfma_f32_16x16x32_bf16 v[112:115], v[212:215], v[154:157], v[112:115]
	v_mfma_f32_16x16x32_bf16 v[100:103], v[204:207], v[166:169], v[100:103]
	v_mfma_f32_16x16x32_bf16 v[96:99], v[212:215], v[166:169], v[96:99]
	v_mfma_f32_16x16x32_bf16 v[84:87], v[204:207], v[188:191], v[84:87]
	v_mfma_f32_16x16x32_bf16 v[80:83], v[212:215], v[188:191], v[80:83]
	v_mfma_f32_16x16x32_bf16 v[68:71], v[204:207], v[196:199], v[68:71]
	v_mfma_f32_16x16x32_bf16 v[64:67], v[212:215], v[196:199], v[64:67]
	v_mfma_f32_16x16x32_bf16 v[116:119], v[208:211], v[158:161], v[116:119]
	s_waitcnt lgkmcnt(0)
	v_mfma_f32_16x16x32_bf16 v[112:115], v[232:235], v[158:161], v[112:115]
	v_mfma_f32_16x16x32_bf16 v[100:103], v[208:211], v[170:173], v[100:103]
	v_mfma_f32_16x16x32_bf16 v[96:99], v[232:235], v[170:173], v[96:99]
	v_mfma_f32_16x16x32_bf16 v[84:87], v[208:211], v[192:195], v[84:87]
	v_mfma_f32_16x16x32_bf16 v[80:83], v[232:235], v[192:195], v[80:83]
	v_mfma_f32_16x16x32_bf16 v[68:71], v[208:211], v[200:203], v[68:71]
	v_mfma_f32_16x16x32_bf16 v[64:67], v[232:235], v[200:203], v[64:67]
	s_mov_b32 m0, s69
	s_barrier
	global_load_lds_dwordx4 v144, s[64:65]
	s_mov_b32 m0, s70
	s_nop 0
	global_load_lds_dwordx4 v146, s[64:65]
	ds_read_b128 v[154:157], v165 offset:16384
	ds_read_b128 v[166:169], v165 offset:18432
	ds_read_b128 v[188:191], v165 offset:20480
	ds_read_b128 v[196:199], v165 offset:22528
	ds_read_b128 v[158:161], v165 offset:17408
	ds_read_b128 v[170:173], v165 offset:19456
	ds_read_b128 v[192:195], v165 offset:21504
	ds_read_b128 v[200:203], v165 offset:23552
	s_barrier
	s_waitcnt lgkmcnt(7)
	v_mfma_f32_16x16x32_bf16 v[60:63], v[128:131], v[154:157], v[60:63]
	v_mfma_f32_16x16x32_bf16 v[56:59], v[136:139], v[154:157], v[56:59]
	s_waitcnt lgkmcnt(6)
	v_mfma_f32_16x16x32_bf16 v[44:47], v[128:131], v[166:169], v[44:47]
	v_mfma_f32_16x16x32_bf16 v[40:43], v[136:139], v[166:169], v[40:43]
	s_waitcnt lgkmcnt(5)
	v_mfma_f32_16x16x32_bf16 v[28:31], v[128:131], v[188:191], v[28:31]
	v_mfma_f32_16x16x32_bf16 v[24:27], v[136:139], v[188:191], v[24:27]
	s_waitcnt lgkmcnt(4)
	v_mfma_f32_16x16x32_bf16 v[12:15], v[128:131], v[196:199], v[12:15]
	v_mfma_f32_16x16x32_bf16 v[8:11], v[136:139], v[196:199], v[8:11]
	s_waitcnt lgkmcnt(3)
	v_mfma_f32_16x16x32_bf16 v[60:63], v[132:135], v[158:161], v[60:63]
	v_mfma_f32_16x16x32_bf16 v[56:59], v[140:143], v[158:161], v[56:59]
	s_waitcnt lgkmcnt(2)
	v_mfma_f32_16x16x32_bf16 v[44:47], v[132:135], v[170:173], v[44:47]
	v_mfma_f32_16x16x32_bf16 v[40:43], v[140:143], v[170:173], v[40:43]
	s_waitcnt lgkmcnt(1)
	v_mfma_f32_16x16x32_bf16 v[28:31], v[132:135], v[192:195], v[28:31]
	v_mfma_f32_16x16x32_bf16 v[24:27], v[140:143], v[192:195], v[24:27]
	s_waitcnt lgkmcnt(0)
	v_mfma_f32_16x16x32_bf16 v[12:15], v[132:135], v[200:203], v[12:15]
	v_mfma_f32_16x16x32_bf16 v[8:11], v[140:143], v[200:203], v[8:11]
	s_barrier
	s_add_u32 s18, s62, 0x18000
	s_addc_u32 s19, s63, 0
	s_add_i32 s28, s29, s68
	s_mov_b32 m0, s28
	s_nop 0
	global_load_lds_dwordx4 v176, s[18:19]
	s_add_i32 m0, s28, 0x2000
	s_nop 0
	global_load_lds_dwordx4 v148, s[18:19]
	s_waitcnt vmcnt(6)
	s_barrier
	v_mfma_f32_16x16x32_bf16 v[52:55], v[204:207], v[154:157], v[52:55]
	v_mfma_f32_16x16x32_bf16 v[48:51], v[212:215], v[154:157], v[48:51]
	v_mfma_f32_16x16x32_bf16 v[36:39], v[204:207], v[166:169], v[36:39]
	v_mfma_f32_16x16x32_bf16 v[32:35], v[212:215], v[166:169], v[32:35]
	v_mfma_f32_16x16x32_bf16 v[20:23], v[204:207], v[188:191], v[20:23]
	v_mfma_f32_16x16x32_bf16 v[16:19], v[212:215], v[188:191], v[16:19]
	v_mfma_f32_16x16x32_bf16 v[4:7], v[204:207], v[196:199], v[4:7]
	v_mfma_f32_16x16x32_bf16 v[0:3], v[212:215], v[196:199], v[0:3]
	v_mfma_f32_16x16x32_bf16 v[52:55], v[208:211], v[158:161], v[52:55]
	v_mfma_f32_16x16x32_bf16 v[48:51], v[232:235], v[158:161], v[48:51]
	v_mfma_f32_16x16x32_bf16 v[36:39], v[208:211], v[170:173], v[36:39]
	v_mfma_f32_16x16x32_bf16 v[32:35], v[232:235], v[170:173], v[32:35]
	v_mfma_f32_16x16x32_bf16 v[20:23], v[208:211], v[192:195], v[20:23]
	v_mfma_f32_16x16x32_bf16 v[16:19], v[232:235], v[192:195], v[16:19]
	v_mfma_f32_16x16x32_bf16 v[4:7], v[208:211], v[200:203], v[4:7]
	v_mfma_f32_16x16x32_bf16 v[0:3], v[232:235], v[200:203], v[0:3]
	s_add_i32 s28, 0, 0x18000
	s_barrier
	s_add_u32 s18, s64, 0x18000
	s_addc_u32 s19, s65, 0
	s_mov_b32 m0, s71
	s_nop 0
	global_load_lds_dwordx4 v144, s[18:19]
	s_mov_b32 m0, s72
	s_nop 0
	global_load_lds_dwordx4 v146, s[18:19]
	ds_read_b128 v[128:131], v174 offset:32768
	ds_read_b128 v[132:135], v174 offset:33792
	ds_read_b128 v[136:139], v174 offset:34816
	ds_read_b128 v[140:143], v174 offset:35840
	ds_read_b128 v[154:157], v165 offset:32768
	ds_read_b128 v[166:169], v165 offset:34816
	ds_read_b128 v[188:191], v165 offset:36864
	ds_read_b128 v[196:199], v165 offset:38912
	ds_read_b128 v[158:161], v165 offset:33792
	ds_read_b128 v[170:173], v165 offset:35840
	ds_read_b128 v[192:195], v165 offset:37888
	ds_read_b128 v[200:203], v165 offset:39936
	s_waitcnt lgkmcnt(8)
	s_barrier
	s_waitcnt lgkmcnt(7)
	v_mfma_f32_16x16x32_bf16 v[124:127], v[128:131], v[154:157], v[124:127]
	v_mfma_f32_16x16x32_bf16 v[120:123], v[136:139], v[154:157], v[120:123]
	s_waitcnt lgkmcnt(6)
	v_mfma_f32_16x16x32_bf16 v[108:111], v[128:131], v[166:169], v[108:111]
	v_mfma_f32_16x16x32_bf16 v[104:107], v[136:139], v[166:169], v[104:107]
	s_waitcnt lgkmcnt(5)
	v_mfma_f32_16x16x32_bf16 v[92:95], v[128:131], v[188:191], v[92:95]
	v_mfma_f32_16x16x32_bf16 v[88:91], v[136:139], v[188:191], v[88:91]
	s_waitcnt lgkmcnt(4)
	v_mfma_f32_16x16x32_bf16 v[76:79], v[128:131], v[196:199], v[76:79]
	v_mfma_f32_16x16x32_bf16 v[72:75], v[136:139], v[196:199], v[72:75]
	s_waitcnt lgkmcnt(3)
	v_mfma_f32_16x16x32_bf16 v[124:127], v[132:135], v[158:161], v[124:127]
	v_mfma_f32_16x16x32_bf16 v[120:123], v[140:143], v[158:161], v[120:123]
	s_waitcnt lgkmcnt(2)
	v_mfma_f32_16x16x32_bf16 v[108:111], v[132:135], v[170:173], v[108:111]
	v_mfma_f32_16x16x32_bf16 v[104:107], v[140:143], v[170:173], v[104:107]
	s_waitcnt lgkmcnt(1)
	v_mfma_f32_16x16x32_bf16 v[92:95], v[132:135], v[192:195], v[92:95]
	v_mfma_f32_16x16x32_bf16 v[88:91], v[140:143], v[192:195], v[88:91]
	s_waitcnt lgkmcnt(0)
	v_mfma_f32_16x16x32_bf16 v[76:79], v[132:135], v[200:203], v[76:79]
	v_mfma_f32_16x16x32_bf16 v[72:75], v[140:143], v[200:203], v[72:75]
	s_barrier
	s_add_i32 s29, 0, 0x1c000
	s_add_i32 s18, s28, s68
	s_add_i32 m0, s18, 0xffffff80
	s_nop 0
	global_load_lds_dwordx4 v176, s[62:63] offset:128
	s_add_i32 m0, s18, 0x1f80
	s_nop 0
	global_load_lds_dwordx4 v148, s[62:63] offset:128
	ds_read_b128 v[204:207], v174 offset:49152
	ds_read_b128 v[208:211], v174 offset:50176
	ds_read_b128 v[212:215], v174 offset:51200
	ds_read_b128 v[232:235], v174 offset:52224
	s_barrier
	s_waitcnt lgkmcnt(3)
	v_mfma_f32_16x16x32_bf16 v[116:119], v[204:207], v[154:157], v[116:119]
	s_waitcnt lgkmcnt(1)
	v_mfma_f32_16x16x32_bf16 v[112:115], v[212:215], v[154:157], v[112:115]
	v_mfma_f32_16x16x32_bf16 v[100:103], v[204:207], v[166:169], v[100:103]
	v_mfma_f32_16x16x32_bf16 v[96:99], v[212:215], v[166:169], v[96:99]
	v_mfma_f32_16x16x32_bf16 v[84:87], v[204:207], v[188:191], v[84:87]
	v_mfma_f32_16x16x32_bf16 v[80:83], v[212:215], v[188:191], v[80:83]
	v_mfma_f32_16x16x32_bf16 v[68:71], v[204:207], v[196:199], v[68:71]
	v_mfma_f32_16x16x32_bf16 v[64:67], v[212:215], v[196:199], v[64:67]
	v_mfma_f32_16x16x32_bf16 v[116:119], v[208:211], v[158:161], v[116:119]
	s_waitcnt lgkmcnt(0)
	v_mfma_f32_16x16x32_bf16 v[112:115], v[232:235], v[158:161], v[112:115]
	v_mfma_f32_16x16x32_bf16 v[100:103], v[208:211], v[170:173], v[100:103]
	v_mfma_f32_16x16x32_bf16 v[96:99], v[232:235], v[170:173], v[96:99]
	v_mfma_f32_16x16x32_bf16 v[84:87], v[208:211], v[192:195], v[84:87]
	v_mfma_f32_16x16x32_bf16 v[80:83], v[232:235], v[192:195], v[80:83]
	v_mfma_f32_16x16x32_bf16 v[68:71], v[208:211], v[200:203], v[68:71]
	v_mfma_f32_16x16x32_bf16 v[64:67], v[232:235], v[200:203], v[64:67]
	s_add_i32 m0, s75, 0xffffff80
	s_barrier
	global_load_lds_dwordx4 v144, s[64:65] offset:128
	s_add_i32 m0, s76, 0xffffff80
	s_nop 0
	global_load_lds_dwordx4 v146, s[64:65] offset:128
	ds_read_b128 v[154:157], v165 offset:49152
	ds_read_b128 v[166:169], v165 offset:51200
	ds_read_b128 v[188:191], v165 offset:53248
	ds_read_b128 v[196:199], v165 offset:55296
	ds_read_b128 v[158:161], v165 offset:50176
	ds_read_b128 v[170:173], v165 offset:52224
	ds_read_b128 v[192:195], v165 offset:54272
	ds_read_b128 v[200:203], v165 offset:56320
	s_barrier
	s_waitcnt lgkmcnt(7)
	v_mfma_f32_16x16x32_bf16 v[60:63], v[128:131], v[154:157], v[60:63]
	v_mfma_f32_16x16x32_bf16 v[56:59], v[136:139], v[154:157], v[56:59]
	s_waitcnt lgkmcnt(6)
	v_mfma_f32_16x16x32_bf16 v[44:47], v[128:131], v[166:169], v[44:47]
	v_mfma_f32_16x16x32_bf16 v[40:43], v[136:139], v[166:169], v[40:43]
	s_waitcnt lgkmcnt(5)
	v_mfma_f32_16x16x32_bf16 v[28:31], v[128:131], v[188:191], v[28:31]
	v_mfma_f32_16x16x32_bf16 v[24:27], v[136:139], v[188:191], v[24:27]
	s_waitcnt lgkmcnt(4)
	v_mfma_f32_16x16x32_bf16 v[12:15], v[128:131], v[196:199], v[12:15]
	v_mfma_f32_16x16x32_bf16 v[8:11], v[136:139], v[196:199], v[8:11]
	s_waitcnt lgkmcnt(3)
	v_mfma_f32_16x16x32_bf16 v[60:63], v[132:135], v[158:161], v[60:63]
	v_mfma_f32_16x16x32_bf16 v[56:59], v[140:143], v[158:161], v[56:59]
	s_waitcnt lgkmcnt(2)
	v_mfma_f32_16x16x32_bf16 v[44:47], v[132:135], v[170:173], v[44:47]
	v_mfma_f32_16x16x32_bf16 v[40:43], v[140:143], v[170:173], v[40:43]
	s_waitcnt lgkmcnt(1)
	v_mfma_f32_16x16x32_bf16 v[28:31], v[132:135], v[192:195], v[28:31]
	v_mfma_f32_16x16x32_bf16 v[24:27], v[140:143], v[192:195], v[24:27]
	s_waitcnt lgkmcnt(0)
	v_mfma_f32_16x16x32_bf16 v[12:15], v[132:135], v[200:203], v[12:15]
	v_mfma_f32_16x16x32_bf16 v[8:11], v[140:143], v[200:203], v[8:11]
	s_barrier
	s_add_u32 s18, s62, 0x18080
	s_addc_u32 s19, s63, 0
	s_add_i32 s28, s29, s68
	s_mov_b32 m0, s28
	s_nop 0
	global_load_lds_dwordx4 v176, s[18:19]
	s_add_i32 m0, s28, 0x2000
	s_nop 0
	global_load_lds_dwordx4 v148, s[18:19]
	s_waitcnt vmcnt(6)
	s_barrier
	v_mfma_f32_16x16x32_bf16 v[52:55], v[204:207], v[154:157], v[52:55]
	v_mfma_f32_16x16x32_bf16 v[48:51], v[212:215], v[154:157], v[48:51]
	v_mfma_f32_16x16x32_bf16 v[36:39], v[204:207], v[166:169], v[36:39]
	v_mfma_f32_16x16x32_bf16 v[32:35], v[212:215], v[166:169], v[32:35]
	v_mfma_f32_16x16x32_bf16 v[20:23], v[204:207], v[188:191], v[20:23]
	v_mfma_f32_16x16x32_bf16 v[16:19], v[212:215], v[188:191], v[16:19]
	v_mfma_f32_16x16x32_bf16 v[4:7], v[204:207], v[196:199], v[4:7]
	v_mfma_f32_16x16x32_bf16 v[0:3], v[212:215], v[196:199], v[0:3]
	v_mfma_f32_16x16x32_bf16 v[52:55], v[208:211], v[158:161], v[52:55]
	v_mfma_f32_16x16x32_bf16 v[48:51], v[232:235], v[158:161], v[48:51]
	v_mfma_f32_16x16x32_bf16 v[36:39], v[208:211], v[170:173], v[36:39]
	v_mfma_f32_16x16x32_bf16 v[32:35], v[232:235], v[170:173], v[32:35]
	v_mfma_f32_16x16x32_bf16 v[20:23], v[208:211], v[192:195], v[20:23]
	v_mfma_f32_16x16x32_bf16 v[16:19], v[232:235], v[192:195], v[16:19]
	v_mfma_f32_16x16x32_bf16 v[4:7], v[208:211], v[200:203], v[4:7]
	v_mfma_f32_16x16x32_bf16 v[0:3], v[232:235], v[200:203], v[0:3]
	s_add_u32 s85, s85, 0x100
	s_addc_u32 s91, s91, 0
	s_cmp_lt_i32 vcc_lo, s67
	s_mov_b64 s[18:19], s[4:5]
	s_mov_b32 s62, vcc_lo
	s_barrier
	s_cbranch_scc1 .LBB0_413
	s_ashr_i32 s4, s66, 2
	v_mov_b32_e32 v128, v163
	v_mov_b32_e32 v166, v162
	s_cmp_eq_u32 s4, 2
	s_cbranch_scc1 .LBB0_416
	s_mul_i32 s13, s4, 0x2280000
	s_mul_hi_i32 s5, s4, 0x2280000
	s_add_u32 s18, s13, 0x5858000
	s_addc_u32 s19, s5, 0
	s_mov_b32 s62, 1.0
	s_branch .LBB0_417

.LBB0_505:
	s_add_u32 s6, s4, 0xfff80080
	s_addc_u32 s7, s5, -1
	s_add_i32 s28, 0, 0x10000
	s_cmp_eq_u32 s72, 28
	s_cselect_b32 s9, s10, s7
	s_cselect_b32 s8, s11, s6
	s_cselect_b32 s7, s63, s71
	s_cselect_b32 s6, s65, s70
	s_add_i32 m0, s17, 0xc000
	s_nop 0
	global_load_lds_dwordx4 v134, s[4:5]
	s_add_i32 m0, s17, 0xe000
	s_nop 0
	global_load_lds_dwordx4 v136, s[4:5]
	ds_read_b128 v[138:141], v174
	ds_read_b128 v[146:149], v174 offset:1024
	ds_read_b128 v[150:153], v174 offset:2048
	ds_read_b128 v[154:157], v174 offset:3072
	ds_read_b128 v[158:161], v145
	ds_read_b128 v[166:169], v145 offset:2048
	ds_read_b128 v[188:191], v145 offset:4096
	ds_read_b128 v[196:199], v145 offset:6144
	ds_read_b128 v[162:165], v145 offset:1024
	ds_read_b128 v[170:173], v145 offset:3072
	ds_read_b128 v[192:195], v145 offset:5120
	ds_read_b128 v[200:203], v145 offset:7168
	s_waitcnt lgkmcnt(8)
	s_barrier
	s_waitcnt lgkmcnt(7)
	v_mfma_f32_16x16x32_bf16 v[124:127], v[138:141], v[158:161], v[124:127]
	v_mfma_f32_16x16x32_bf16 v[120:123], v[150:153], v[158:161], v[120:123]
	s_waitcnt lgkmcnt(6)
	v_mfma_f32_16x16x32_bf16 v[116:119], v[138:141], v[166:169], v[116:119]
	v_mfma_f32_16x16x32_bf16 v[108:111], v[150:153], v[166:169], v[108:111]
	s_waitcnt lgkmcnt(5)
	v_mfma_f32_16x16x32_bf16 v[100:103], v[138:141], v[188:191], v[100:103]
	v_mfma_f32_16x16x32_bf16 v[92:95], v[150:153], v[188:191], v[92:95]
	s_waitcnt lgkmcnt(4)
	v_mfma_f32_16x16x32_bf16 v[84:87], v[138:141], v[196:199], v[84:87]
	v_mfma_f32_16x16x32_bf16 v[76:79], v[150:153], v[196:199], v[76:79]
	s_waitcnt lgkmcnt(3)
	v_mfma_f32_16x16x32_bf16 v[124:127], v[146:149], v[162:165], v[124:127]
	v_mfma_f32_16x16x32_bf16 v[120:123], v[154:157], v[162:165], v[120:123]
	s_waitcnt lgkmcnt(2)
	v_mfma_f32_16x16x32_bf16 v[116:119], v[146:149], v[170:173], v[116:119]
	v_mfma_f32_16x16x32_bf16 v[108:111], v[154:157], v[170:173], v[108:111]
	s_waitcnt lgkmcnt(1)
	v_mfma_f32_16x16x32_bf16 v[100:103], v[146:149], v[192:195], v[100:103]
	v_mfma_f32_16x16x32_bf16 v[92:95], v[154:157], v[192:195], v[92:95]
	s_waitcnt lgkmcnt(0)
	v_mfma_f32_16x16x32_bf16 v[84:87], v[146:149], v[200:203], v[84:87]
	v_mfma_f32_16x16x32_bf16 v[76:79], v[154:157], v[200:203], v[76:79]
	s_barrier
	s_add_i32 s29, 0, 0x14000
	s_add_i32 s28, s28, s77
	s_mov_b32 m0, s28
	s_nop 0
	global_load_lds_dwordx4 v176, s[6:7]
	s_add_i32 m0, s28, 0x2000
	s_nop 0
	global_load_lds_dwordx4 v132, s[6:7]
	ds_read_b128 v[204:207], v174 offset:16384
	ds_read_b128 v[208:211], v174 offset:17408
	ds_read_b128 v[212:215], v174 offset:18432
	ds_read_b128 v[232:235], v174 offset:19456
	s_barrier
	s_waitcnt lgkmcnt(3)
	v_mfma_f32_16x16x32_bf16 v[112:115], v[204:207], v[158:161], v[112:115]
	s_waitcnt lgkmcnt(1)
	v_mfma_f32_16x16x32_bf16 v[104:107], v[212:215], v[158:161], v[104:107]
	v_mfma_f32_16x16x32_bf16 v[96:99], v[204:207], v[166:169], v[96:99]
	v_mfma_f32_16x16x32_bf16 v[88:91], v[212:215], v[166:169], v[88:91]
	v_mfma_f32_16x16x32_bf16 v[80:83], v[204:207], v[188:191], v[80:83]
	v_mfma_f32_16x16x32_bf16 v[72:75], v[212:215], v[188:191], v[72:75]
	v_mfma_f32_16x16x32_bf16 v[68:71], v[204:207], v[196:199], v[68:71]
	v_mfma_f32_16x16x32_bf16 v[64:67], v[212:215], v[196:199], v[64:67]
	v_mfma_f32_16x16x32_bf16 v[112:115], v[208:211], v[162:165], v[112:115]
	s_waitcnt lgkmcnt(0)
	v_mfma_f32_16x16x32_bf16 v[104:107], v[232:235], v[162:165], v[104:107]
	v_mfma_f32_16x16x32_bf16 v[96:99], v[208:211], v[170:173], v[96:99]
	v_mfma_f32_16x16x32_bf16 v[88:91], v[232:235], v[170:173], v[88:91]
	v_mfma_f32_16x16x32_bf16 v[80:83], v[208:211], v[192:195], v[80:83]
	v_mfma_f32_16x16x32_bf16 v[72:75], v[232:235], v[192:195], v[72:75]
	v_mfma_f32_16x16x32_bf16 v[68:71], v[208:211], v[200:203], v[68:71]
	v_mfma_f32_16x16x32_bf16 v[64:67], v[232:235], v[200:203], v[64:67]
	s_mov_b32 m0, s17
	s_barrier
	global_load_lds_dwordx4 v128, s[8:9]
	s_mov_b32 m0, s19
	s_nop 0
	global_load_lds_dwordx4 v130, s[8:9]
	ds_read_b128 v[158:161], v145 offset:16384
	ds_read_b128 v[166:169], v145 offset:18432
	ds_read_b128 v[188:191], v145 offset:20480
	ds_read_b128 v[196:199], v145 offset:22528
	ds_read_b128 v[162:165], v145 offset:17408
	ds_read_b128 v[170:173], v145 offset:19456
	ds_read_b128 v[192:195], v145 offset:21504
	ds_read_b128 v[200:203], v145 offset:23552
	s_barrier
	s_waitcnt lgkmcnt(7)
	v_mfma_f32_16x16x32_bf16 v[60:63], v[138:141], v[158:161], v[60:63]
	v_mfma_f32_16x16x32_bf16 v[56:59], v[150:153], v[158:161], v[56:59]
	s_waitcnt lgkmcnt(6)
	v_mfma_f32_16x16x32_bf16 v[52:55], v[138:141], v[166:169], v[52:55]
	v_mfma_f32_16x16x32_bf16 v[44:47], v[150:153], v[166:169], v[44:47]
	s_waitcnt lgkmcnt(5)
	v_mfma_f32_16x16x32_bf16 v[36:39], v[138:141], v[188:191], v[36:39]
	v_mfma_f32_16x16x32_bf16 v[28:31], v[150:153], v[188:191], v[28:31]
	s_waitcnt lgkmcnt(4)
	v_mfma_f32_16x16x32_bf16 v[20:23], v[138:141], v[196:199], v[20:23]
	v_mfma_f32_16x16x32_bf16 v[12:15], v[150:153], v[196:199], v[12:15]
	s_waitcnt lgkmcnt(3)
	v_mfma_f32_16x16x32_bf16 v[60:63], v[146:149], v[162:165], v[60:63]
	v_mfma_f32_16x16x32_bf16 v[56:59], v[154:157], v[162:165], v[56:59]
	s_waitcnt lgkmcnt(2)
	v_mfma_f32_16x16x32_bf16 v[52:55], v[146:149], v[170:173], v[52:55]
	v_mfma_f32_16x16x32_bf16 v[44:47], v[154:157], v[170:173], v[44:47]
	s_waitcnt lgkmcnt(1)
	v_mfma_f32_16x16x32_bf16 v[36:39], v[146:149], v[192:195], v[36:39]
	v_mfma_f32_16x16x32_bf16 v[28:31], v[154:157], v[192:195], v[28:31]
	s_waitcnt lgkmcnt(0)
	v_mfma_f32_16x16x32_bf16 v[20:23], v[146:149], v[200:203], v[20:23]
	v_mfma_f32_16x16x32_bf16 v[12:15], v[154:157], v[200:203], v[12:15]
	s_barrier
	s_add_u32 vcc_lo, s6, 0x80000
	s_addc_u32 vcc_hi, s7, 0
	s_add_i32 s28, s29, s77
	s_mov_b32 m0, s28
	s_nop 0
	global_load_lds_dwordx4 v176, vcc
	s_add_i32 m0, s28, 0x2000
	s_nop 0
	global_load_lds_dwordx4 v132, vcc
	s_waitcnt vmcnt(6)
	s_barrier
	v_mfma_f32_16x16x32_bf16 v[48:51], v[204:207], v[158:161], v[48:51]
	v_mfma_f32_16x16x32_bf16 v[40:43], v[212:215], v[158:161], v[40:43]
	v_mfma_f32_16x16x32_bf16 v[32:35], v[204:207], v[166:169], v[32:35]
	v_mfma_f32_16x16x32_bf16 v[24:27], v[212:215], v[166:169], v[24:27]
	v_mfma_f32_16x16x32_bf16 v[16:19], v[204:207], v[188:191], v[16:19]
	v_mfma_f32_16x16x32_bf16 v[8:11], v[212:215], v[188:191], v[8:11]
	v_mfma_f32_16x16x32_bf16 v[4:7], v[204:207], v[196:199], v[4:7]
	v_mfma_f32_16x16x32_bf16 v[0:3], v[212:215], v[196:199], v[0:3]
	v_mfma_f32_16x16x32_bf16 v[48:51], v[208:211], v[162:165], v[48:51]
	v_mfma_f32_16x16x32_bf16 v[40:43], v[232:235], v[162:165], v[40:43]
	v_mfma_f32_16x16x32_bf16 v[32:35], v[208:211], v[170:173], v[32:35]
	v_mfma_f32_16x16x32_bf16 v[24:27], v[232:235], v[170:173], v[24:27]
	v_mfma_f32_16x16x32_bf16 v[16:19], v[208:211], v[192:195], v[16:19]
	v_mfma_f32_16x16x32_bf16 v[8:11], v[232:235], v[192:195], v[8:11]
	v_mfma_f32_16x16x32_bf16 v[4:7], v[208:211], v[200:203], v[4:7]
	v_mfma_f32_16x16x32_bf16 v[0:3], v[232:235], v[200:203], v[0:3]
	s_add_i32 s28, 0, 0x18000
	s_barrier
	s_add_u32 s98, s8, 0x80000
	s_addc_u32 s99, s9, 0
	s_mov_b32 m0, s78
	s_nop 0
	global_load_lds_dwordx4 v128, s[98:99]
	s_mov_b32 m0, s79
	s_nop 0
	global_load_lds_dwordx4 v130, s[98:99]
	ds_read_b128 v[138:141], v174 offset:32768
	ds_read_b128 v[146:149], v174 offset:33792
	ds_read_b128 v[150:153], v174 offset:34816
	ds_read_b128 v[154:157], v174 offset:35840
	ds_read_b128 v[158:161], v145 offset:32768
	ds_read_b128 v[166:169], v145 offset:34816
	ds_read_b128 v[188:191], v145 offset:36864
	ds_read_b128 v[196:199], v145 offset:38912
	ds_read_b128 v[162:165], v145 offset:33792
	ds_read_b128 v[170:173], v145 offset:35840
	ds_read_b128 v[192:195], v145 offset:37888
	ds_read_b128 v[200:203], v145 offset:39936
	s_waitcnt lgkmcnt(8)
	s_barrier
	s_waitcnt lgkmcnt(7)
	v_mfma_f32_16x16x32_bf16 v[124:127], v[138:141], v[158:161], v[124:127]
	v_mfma_f32_16x16x32_bf16 v[120:123], v[150:153], v[158:161], v[120:123]
	s_waitcnt lgkmcnt(6)
	v_mfma_f32_16x16x32_bf16 v[116:119], v[138:141], v[166:169], v[116:119]
	v_mfma_f32_16x16x32_bf16 v[108:111], v[150:153], v[166:169], v[108:111]
	s_waitcnt lgkmcnt(5)
	v_mfma_f32_16x16x32_bf16 v[100:103], v[138:141], v[188:191], v[100:103]
	v_mfma_f32_16x16x32_bf16 v[92:95], v[150:153], v[188:191], v[92:95]
	s_waitcnt lgkmcnt(4)
	v_mfma_f32_16x16x32_bf16 v[84:87], v[138:141], v[196:199], v[84:87]
	v_mfma_f32_16x16x32_bf16 v[76:79], v[150:153], v[196:199], v[76:79]
	s_waitcnt lgkmcnt(3)
	v_mfma_f32_16x16x32_bf16 v[124:127], v[146:149], v[162:165], v[124:127]
	v_mfma_f32_16x16x32_bf16 v[120:123], v[154:157], v[162:165], v[120:123]
	s_waitcnt lgkmcnt(2)
	v_mfma_f32_16x16x32_bf16 v[116:119], v[146:149], v[170:173], v[116:119]
	v_mfma_f32_16x16x32_bf16 v[108:111], v[154:157], v[170:173], v[108:111]
	s_waitcnt lgkmcnt(1)
	v_mfma_f32_16x16x32_bf16 v[100:103], v[146:149], v[192:195], v[100:103]
	v_mfma_f32_16x16x32_bf16 v[92:95], v[154:157], v[192:195], v[92:95]
	s_waitcnt lgkmcnt(0)
	v_mfma_f32_16x16x32_bf16 v[84:87], v[146:149], v[200:203], v[84:87]
	v_mfma_f32_16x16x32_bf16 v[76:79], v[154:157], v[200:203], v[76:79]
	s_barrier
	s_add_i32 s100, 0, 0x1c000
	s_add_i32 s101, s28, s77
	s_add_i32 m0, s101, 0xffffff80
	s_nop 0
	global_load_lds_dwordx4 v176, s[6:7] offset:128
	s_add_i32 m0, s101, 0x1f80
	s_nop 0
	global_load_lds_dwordx4 v132, s[6:7] offset:128
	ds_read_b128 v[204:207], v174 offset:49152
	ds_read_b128 v[208:211], v174 offset:50176
	ds_read_b128 v[212:215], v174 offset:51200
	ds_read_b128 v[232:235], v174 offset:52224
	s_barrier
	s_waitcnt lgkmcnt(3)
	v_mfma_f32_16x16x32_bf16 v[112:115], v[204:207], v[158:161], v[112:115]
	s_waitcnt lgkmcnt(1)
	v_mfma_f32_16x16x32_bf16 v[104:107], v[212:215], v[158:161], v[104:107]
	v_mfma_f32_16x16x32_bf16 v[96:99], v[204:207], v[166:169], v[96:99]
	v_mfma_f32_16x16x32_bf16 v[88:91], v[212:215], v[166:169], v[88:91]
	v_mfma_f32_16x16x32_bf16 v[80:83], v[204:207], v[188:191], v[80:83]
	v_mfma_f32_16x16x32_bf16 v[72:75], v[212:215], v[188:191], v[72:75]
	v_mfma_f32_16x16x32_bf16 v[68:71], v[204:207], v[196:199], v[68:71]
	v_mfma_f32_16x16x32_bf16 v[64:67], v[212:215], v[196:199], v[64:67]
	v_mfma_f32_16x16x32_bf16 v[112:115], v[208:211], v[162:165], v[112:115]
	s_waitcnt lgkmcnt(0)
	v_mfma_f32_16x16x32_bf16 v[104:107], v[232:235], v[162:165], v[104:107]
	v_mfma_f32_16x16x32_bf16 v[96:99], v[208:211], v[170:173], v[96:99]
	v_mfma_f32_16x16x32_bf16 v[88:91], v[232:235], v[170:173], v[88:91]
	v_mfma_f32_16x16x32_bf16 v[80:83], v[208:211], v[192:195], v[80:83]
	v_mfma_f32_16x16x32_bf16 v[72:75], v[232:235], v[192:195], v[72:75]
	v_mfma_f32_16x16x32_bf16 v[68:71], v[208:211], v[200:203], v[68:71]
	v_mfma_f32_16x16x32_bf16 v[64:67], v[232:235], v[200:203], v[64:67]
	s_add_i32 m0, s82, 0xffffff80
	s_barrier
	global_load_lds_dwordx4 v128, s[8:9] offset:128
	s_add_i32 m0, s83, 0xffffff80
	s_nop 0
	global_load_lds_dwordx4 v130, s[8:9] offset:128
	ds_read_b128 v[158:161], v145 offset:49152
	ds_read_b128 v[166:169], v145 offset:51200
	ds_read_b128 v[188:191], v145 offset:53248
	ds_read_b128 v[196:199], v145 offset:55296
	ds_read_b128 v[162:165], v145 offset:50176
	ds_read_b128 v[170:173], v145 offset:52224
	ds_read_b128 v[192:195], v145 offset:54272
	ds_read_b128 v[200:203], v145 offset:56320
	s_barrier
	s_waitcnt lgkmcnt(7)
	v_mfma_f32_16x16x32_bf16 v[60:63], v[138:141], v[158:161], v[60:63]
	v_mfma_f32_16x16x32_bf16 v[56:59], v[150:153], v[158:161], v[56:59]
	s_waitcnt lgkmcnt(6)
	v_mfma_f32_16x16x32_bf16 v[52:55], v[138:141], v[166:169], v[52:55]
	v_mfma_f32_16x16x32_bf16 v[44:47], v[150:153], v[166:169], v[44:47]
	s_waitcnt lgkmcnt(5)
	v_mfma_f32_16x16x32_bf16 v[36:39], v[138:141], v[188:191], v[36:39]
	v_mfma_f32_16x16x32_bf16 v[28:31], v[150:153], v[188:191], v[28:31]
	s_waitcnt lgkmcnt(4)
	v_mfma_f32_16x16x32_bf16 v[20:23], v[138:141], v[196:199], v[20:23]
	v_mfma_f32_16x16x32_bf16 v[12:15], v[150:153], v[196:199], v[12:15]
	s_waitcnt lgkmcnt(3)
	v_mfma_f32_16x16x32_bf16 v[60:63], v[146:149], v[162:165], v[60:63]
	v_mfma_f32_16x16x32_bf16 v[56:59], v[154:157], v[162:165], v[56:59]
	s_waitcnt lgkmcnt(2)
	v_mfma_f32_16x16x32_bf16 v[52:55], v[146:149], v[170:173], v[52:55]
	v_mfma_f32_16x16x32_bf16 v[44:47], v[154:157], v[170:173], v[44:47]
	s_waitcnt lgkmcnt(1)
	v_mfma_f32_16x16x32_bf16 v[36:39], v[146:149], v[192:195], v[36:39]
	v_mfma_f32_16x16x32_bf16 v[28:31], v[154:157], v[192:195], v[28:31]
	s_waitcnt lgkmcnt(0)
	v_mfma_f32_16x16x32_bf16 v[20:23], v[146:149], v[200:203], v[20:23]
	v_mfma_f32_16x16x32_bf16 v[12:15], v[154:157], v[200:203], v[12:15]
	s_barrier
	s_add_u32 s6, s6, 0x80080
	s_addc_u32 s7, s7, 0
	s_add_i32 s100, s100, s77
	s_mov_b32 m0, s100
	s_nop 0
	global_load_lds_dwordx4 v176, s[6:7]
	s_add_i32 m0, s100, 0x2000
	s_nop 0
	global_load_lds_dwordx4 v132, s[6:7]
	s_waitcnt vmcnt(6)
	s_barrier
	v_mfma_f32_16x16x32_bf16 v[48:51], v[204:207], v[158:161], v[48:51]
	v_mfma_f32_16x16x32_bf16 v[40:43], v[212:215], v[158:161], v[40:43]
	v_mfma_f32_16x16x32_bf16 v[32:35], v[204:207], v[166:169], v[32:35]
	v_mfma_f32_16x16x32_bf16 v[24:27], v[212:215], v[166:169], v[24:27]
	v_mfma_f32_16x16x32_bf16 v[16:19], v[204:207], v[188:191], v[16:19]
	v_mfma_f32_16x16x32_bf16 v[8:11], v[212:215], v[188:191], v[8:11]
	v_mfma_f32_16x16x32_bf16 v[4:7], v[204:207], v[196:199], v[4:7]
	v_mfma_f32_16x16x32_bf16 v[0:3], v[212:215], v[196:199], v[0:3]
	v_mfma_f32_16x16x32_bf16 v[48:51], v[208:211], v[162:165], v[48:51]
	v_mfma_f32_16x16x32_bf16 v[40:43], v[232:235], v[162:165], v[40:43]
	v_mfma_f32_16x16x32_bf16 v[32:35], v[208:211], v[170:173], v[32:35]
	v_mfma_f32_16x16x32_bf16 v[24:27], v[232:235], v[170:173], v[24:27]
	v_mfma_f32_16x16x32_bf16 v[16:19], v[208:211], v[192:195], v[16:19]
	v_mfma_f32_16x16x32_bf16 v[8:11], v[232:235], v[192:195], v[8:11]
	v_mfma_f32_16x16x32_bf16 v[4:7], v[208:211], v[200:203], v[4:7]
	v_mfma_f32_16x16x32_bf16 v[0:3], v[232:235], v[200:203], v[0:3]
	s_add_i32 s72, s72, 2
	s_add_u32 s4, s4, 0x100
	s_addc_u32 s5, s5, 0
	s_add_u32 s70, s70, 0x100
	s_addc_u32 s71, s71, 0
	s_cmp_lt_u32 s72, 30
	s_barrier
	s_cbranch_scc1 .LBB0_505
	v_mov_b32_e32 v147, v142
	v_mov_b32_e32 v146, v143
	s_cmp_lt_i32 s16, 12
	s_mov_b64 s[4:5], -1
	s_cbranch_scc1 .LBB0_1052
	s_lshl_b32 s4, s18, 8
	s_add_i32 s4, s4, s80
	v_add_u32_e32 v149, s4, v147
	s_lshl_b32 s4, s16, 8
	s_add_i32 s4, s84, s4
	v_lshl_add_u32 v138, v146, 3, s4
	v_mad_i64_i32 v[140:141], s[4:5], v149, s97, 0
	v_cmp_gt_i32_e32 vcc, s34, v138
	s_and_saveexec_b64 s[10:11], vcc
	s_cbranch_execz .LBB0_541
	v_cmp_lt_i32_e64 s[8:9], 63, v138
	v_cmp_gt_u32_e64 s[4:5], s93, v138
	v_cmp_gt_u32_e64 s[6:7], s96, v138
	s_and_saveexec_b64 s[70:71], s[8:9]
	s_xor_b64 s[70:71], exec, s[70:71]
	s_cbranch_execz .LBB0_510
	v_mul_f32_e32 v139, 0xbfb8aa3b, v124
	v_exp_f32_e32 v139, v139
	s_nop 0
	v_add_f32_e32 v139, 1.0, v139
	v_rcp_f32_e32 v139, v139
	s_nop 0
	v_cndmask_b32_e64 v139, 0, v139, s[6:7]
	v_cndmask_b32_e64 v139, v139, v124, s[4:5]
	s_andn2_saveexec_b64 s[70:71], s[70:71]
	s_cbranch_execz .LBB0_512
	s_branch .LBB0_511

.LBB0_1114:
	s_add_i32 vcc_hi, s66, 2
	s_add_u32 s28, s64, 0x80
	s_addc_u32 s29, s65, 0
	s_add_i32 s88, 0, 0x10000
	s_cmp_eq_u32 s85, s66
	s_cselect_b32 s66, s4, s28
	s_cselect_b32 s67, s5, s29
	s_cselect_b32 s69, s7, vcc_lo
	s_cselect_b32 s68, s6, s91
	s_add_i32 m0, s70, 0xc000
	s_nop 0
	global_load_lds_dwordx4 v158, s[64:65]
	s_add_i32 m0, s70, 0xe000
	s_nop 0
	global_load_lds_dwordx4 v160, s[64:65]
	ds_read_b128 v[128:131], v174
	ds_read_b128 v[132:135], v174 offset:1024
	ds_read_b128 v[136:139], v174 offset:2048
	ds_read_b128 v[140:143], v174 offset:3072
	ds_read_b128 v[144:147], v195
	ds_read_b128 v[162:165], v195 offset:2048
	ds_read_b128 v[170:173], v195 offset:4096
	ds_read_b128 v[196:199], v195 offset:6144
	ds_read_b128 v[148:151], v195 offset:1024
	ds_read_b128 v[166:169], v195 offset:3072
	ds_read_b128 v[188:191], v195 offset:5120
	ds_read_b128 v[200:203], v195 offset:7168
	s_waitcnt lgkmcnt(8)
	s_barrier
	s_waitcnt lgkmcnt(7)
	v_mfma_f32_16x16x32_bf16 v[124:127], v[128:131], v[144:147], v[124:127]
	v_mfma_f32_16x16x32_bf16 v[120:123], v[136:139], v[144:147], v[120:123]
	s_waitcnt lgkmcnt(6)
	v_mfma_f32_16x16x32_bf16 v[108:111], v[128:131], v[162:165], v[108:111]
	v_mfma_f32_16x16x32_bf16 v[104:107], v[136:139], v[162:165], v[104:107]
	s_waitcnt lgkmcnt(5)
	v_mfma_f32_16x16x32_bf16 v[92:95], v[128:131], v[170:173], v[92:95]
	v_mfma_f32_16x16x32_bf16 v[88:91], v[136:139], v[170:173], v[88:91]
	s_waitcnt lgkmcnt(4)
	v_mfma_f32_16x16x32_bf16 v[76:79], v[128:131], v[196:199], v[76:79]
	v_mfma_f32_16x16x32_bf16 v[72:75], v[136:139], v[196:199], v[72:75]
	s_waitcnt lgkmcnt(3)
	v_mfma_f32_16x16x32_bf16 v[124:127], v[132:135], v[148:151], v[124:127]
	v_mfma_f32_16x16x32_bf16 v[120:123], v[140:143], v[148:151], v[120:123]
	s_waitcnt lgkmcnt(2)
	v_mfma_f32_16x16x32_bf16 v[108:111], v[132:135], v[166:169], v[108:111]
	v_mfma_f32_16x16x32_bf16 v[104:107], v[140:143], v[166:169], v[104:107]
	s_waitcnt lgkmcnt(1)
	v_mfma_f32_16x16x32_bf16 v[92:95], v[132:135], v[188:191], v[92:95]
	v_mfma_f32_16x16x32_bf16 v[88:91], v[140:143], v[188:191], v[88:91]
	s_waitcnt lgkmcnt(0)
	v_mfma_f32_16x16x32_bf16 v[76:79], v[132:135], v[200:203], v[76:79]
	v_mfma_f32_16x16x32_bf16 v[72:75], v[140:143], v[200:203], v[72:75]
	s_barrier
	s_add_i32 s28, 0, 0x14000
	s_add_i32 s29, s88, s47
	s_mov_b32 m0, s29
	s_nop 0
	global_load_lds_dwordx4 v176, s[68:69]
	s_add_i32 m0, s29, 0x2000
	s_nop 0
	global_load_lds_dwordx4 v156, s[68:69]
	ds_read_b128 v[204:207], v174 offset:16384
	ds_read_b128 v[208:211], v174 offset:17408
	ds_read_b128 v[212:215], v174 offset:18432
	ds_read_b128 v[232:235], v174 offset:19456
	s_barrier
	s_waitcnt lgkmcnt(3)
	v_mfma_f32_16x16x32_bf16 v[116:119], v[204:207], v[144:147], v[116:119]
	s_waitcnt lgkmcnt(1)
	v_mfma_f32_16x16x32_bf16 v[112:115], v[212:215], v[144:147], v[112:115]
	v_mfma_f32_16x16x32_bf16 v[100:103], v[204:207], v[162:165], v[100:103]
	v_mfma_f32_16x16x32_bf16 v[96:99], v[212:215], v[162:165], v[96:99]
	v_mfma_f32_16x16x32_bf16 v[84:87], v[204:207], v[170:173], v[84:87]
	v_mfma_f32_16x16x32_bf16 v[80:83], v[212:215], v[170:173], v[80:83]
	v_mfma_f32_16x16x32_bf16 v[68:71], v[204:207], v[196:199], v[68:71]
	v_mfma_f32_16x16x32_bf16 v[64:67], v[212:215], v[196:199], v[64:67]
	v_mfma_f32_16x16x32_bf16 v[116:119], v[208:211], v[148:151], v[116:119]
	s_waitcnt lgkmcnt(0)
	v_mfma_f32_16x16x32_bf16 v[112:115], v[232:235], v[148:151], v[112:115]
	v_mfma_f32_16x16x32_bf16 v[100:103], v[208:211], v[166:169], v[100:103]
	v_mfma_f32_16x16x32_bf16 v[96:99], v[232:235], v[166:169], v[96:99]
	v_mfma_f32_16x16x32_bf16 v[84:87], v[208:211], v[188:191], v[84:87]
	v_mfma_f32_16x16x32_bf16 v[80:83], v[232:235], v[188:191], v[80:83]
	v_mfma_f32_16x16x32_bf16 v[68:71], v[208:211], v[200:203], v[68:71]
	v_mfma_f32_16x16x32_bf16 v[64:67], v[232:235], v[200:203], v[64:67]
	s_mov_b32 m0, s70
	s_barrier
	global_load_lds_dwordx4 v152, s[66:67]
	s_mov_b32 m0, s71
	s_nop 0
	global_load_lds_dwordx4 v154, s[66:67]
	ds_read_b128 v[144:147], v195 offset:16384
	ds_read_b128 v[162:165], v195 offset:18432
	ds_read_b128 v[170:173], v195 offset:20480
	ds_read_b128 v[196:199], v195 offset:22528
	ds_read_b128 v[148:151], v195 offset:17408
	ds_read_b128 v[166:169], v195 offset:19456
	ds_read_b128 v[188:191], v195 offset:21504
	ds_read_b128 v[200:203], v195 offset:23552
	s_barrier
	s_waitcnt lgkmcnt(7)
	v_mfma_f32_16x16x32_bf16 v[60:63], v[128:131], v[144:147], v[60:63]
	v_mfma_f32_16x16x32_bf16 v[56:59], v[136:139], v[144:147], v[56:59]
	s_waitcnt lgkmcnt(6)
	v_mfma_f32_16x16x32_bf16 v[44:47], v[128:131], v[162:165], v[44:47]
	v_mfma_f32_16x16x32_bf16 v[40:43], v[136:139], v[162:165], v[40:43]
	s_waitcnt lgkmcnt(5)
	v_mfma_f32_16x16x32_bf16 v[28:31], v[128:131], v[170:173], v[28:31]
	v_mfma_f32_16x16x32_bf16 v[24:27], v[136:139], v[170:173], v[24:27]
	s_waitcnt lgkmcnt(4)
	v_mfma_f32_16x16x32_bf16 v[12:15], v[128:131], v[196:199], v[12:15]
	v_mfma_f32_16x16x32_bf16 v[8:11], v[136:139], v[196:199], v[8:11]
	s_waitcnt lgkmcnt(3)
	v_mfma_f32_16x16x32_bf16 v[60:63], v[132:135], v[148:151], v[60:63]
	v_mfma_f32_16x16x32_bf16 v[56:59], v[140:143], v[148:151], v[56:59]
	s_waitcnt lgkmcnt(2)
	v_mfma_f32_16x16x32_bf16 v[44:47], v[132:135], v[166:169], v[44:47]
	v_mfma_f32_16x16x32_bf16 v[40:43], v[140:143], v[166:169], v[40:43]
	s_waitcnt lgkmcnt(1)
	v_mfma_f32_16x16x32_bf16 v[28:31], v[132:135], v[188:191], v[28:31]
	v_mfma_f32_16x16x32_bf16 v[24:27], v[140:143], v[188:191], v[24:27]
	s_waitcnt lgkmcnt(0)
	v_mfma_f32_16x16x32_bf16 v[12:15], v[132:135], v[200:203], v[12:15]
	v_mfma_f32_16x16x32_bf16 v[8:11], v[140:143], v[200:203], v[8:11]
	s_barrier
	s_add_u32 s98, s68, s58
	s_addc_u32 s99, s69, 0
	s_add_i32 s28, s28, s47
	s_mov_b32 m0, s28
	s_nop 0
	global_load_lds_dwordx4 v176, s[98:99]
	s_add_i32 m0, s28, 0x2000
	s_nop 0
	global_load_lds_dwordx4 v156, s[98:99]
	s_waitcnt vmcnt(6)
	s_barrier
	v_mfma_f32_16x16x32_bf16 v[52:55], v[204:207], v[144:147], v[52:55]
	v_mfma_f32_16x16x32_bf16 v[48:51], v[212:215], v[144:147], v[48:51]
	v_mfma_f32_16x16x32_bf16 v[36:39], v[204:207], v[162:165], v[36:39]
	v_mfma_f32_16x16x32_bf16 v[32:35], v[212:215], v[162:165], v[32:35]
	v_mfma_f32_16x16x32_bf16 v[20:23], v[204:207], v[170:173], v[20:23]
	v_mfma_f32_16x16x32_bf16 v[16:19], v[212:215], v[170:173], v[16:19]
	v_mfma_f32_16x16x32_bf16 v[4:7], v[204:207], v[196:199], v[4:7]
	v_mfma_f32_16x16x32_bf16 v[0:3], v[212:215], v[196:199], v[0:3]
	v_mfma_f32_16x16x32_bf16 v[52:55], v[208:211], v[148:151], v[52:55]
	v_mfma_f32_16x16x32_bf16 v[48:51], v[232:235], v[148:151], v[48:51]
	v_mfma_f32_16x16x32_bf16 v[36:39], v[208:211], v[166:169], v[36:39]
	v_mfma_f32_16x16x32_bf16 v[32:35], v[232:235], v[166:169], v[32:35]
	v_mfma_f32_16x16x32_bf16 v[20:23], v[208:211], v[188:191], v[20:23]
	v_mfma_f32_16x16x32_bf16 v[16:19], v[232:235], v[188:191], v[16:19]
	v_mfma_f32_16x16x32_bf16 v[4:7], v[208:211], v[200:203], v[4:7]
	v_mfma_f32_16x16x32_bf16 v[0:3], v[232:235], v[200:203], v[0:3]
	s_add_i32 s28, 0, 0x18000
	s_barrier
	s_add_u32 s100, s66, s58
	s_addc_u32 s101, s67, 0
	s_mov_b32 m0, s72
	s_nop 0
	global_load_lds_dwordx4 v152, s[100:101]
	s_mov_b32 m0, s73
	s_nop 0
	global_load_lds_dwordx4 v154, s[100:101]
	ds_read_b128 v[128:131], v174 offset:32768
	ds_read_b128 v[132:135], v174 offset:33792
	ds_read_b128 v[136:139], v174 offset:34816
	ds_read_b128 v[140:143], v174 offset:35840
	ds_read_b128 v[144:147], v195 offset:32768
	ds_read_b128 v[162:165], v195 offset:34816
	ds_read_b128 v[170:173], v195 offset:36864
	ds_read_b128 v[196:199], v195 offset:38912
	ds_read_b128 v[148:151], v195 offset:33792
	ds_read_b128 v[166:169], v195 offset:35840
	ds_read_b128 v[188:191], v195 offset:37888
	ds_read_b128 v[200:203], v195 offset:39936
	s_waitcnt lgkmcnt(8)
	s_barrier
	s_waitcnt lgkmcnt(7)
	v_mfma_f32_16x16x32_bf16 v[124:127], v[128:131], v[144:147], v[124:127]
	v_mfma_f32_16x16x32_bf16 v[120:123], v[136:139], v[144:147], v[120:123]
	s_waitcnt lgkmcnt(6)
	v_mfma_f32_16x16x32_bf16 v[108:111], v[128:131], v[162:165], v[108:111]
	v_mfma_f32_16x16x32_bf16 v[104:107], v[136:139], v[162:165], v[104:107]
	s_waitcnt lgkmcnt(5)
	v_mfma_f32_16x16x32_bf16 v[92:95], v[128:131], v[170:173], v[92:95]
	v_mfma_f32_16x16x32_bf16 v[88:91], v[136:139], v[170:173], v[88:91]
	s_waitcnt lgkmcnt(4)
	v_mfma_f32_16x16x32_bf16 v[76:79], v[128:131], v[196:199], v[76:79]
	v_mfma_f32_16x16x32_bf16 v[72:75], v[136:139], v[196:199], v[72:75]
	s_waitcnt lgkmcnt(3)
	v_mfma_f32_16x16x32_bf16 v[124:127], v[132:135], v[148:151], v[124:127]
	v_mfma_f32_16x16x32_bf16 v[120:123], v[140:143], v[148:151], v[120:123]
	s_waitcnt lgkmcnt(2)
	v_mfma_f32_16x16x32_bf16 v[108:111], v[132:135], v[166:169], v[108:111]
	v_mfma_f32_16x16x32_bf16 v[104:107], v[140:143], v[166:169], v[104:107]
	s_waitcnt lgkmcnt(1)
	v_mfma_f32_16x16x32_bf16 v[92:95], v[132:135], v[188:191], v[92:95]
	v_mfma_f32_16x16x32_bf16 v[88:91], v[140:143], v[188:191], v[88:91]
	s_waitcnt lgkmcnt(0)
	v_mfma_f32_16x16x32_bf16 v[76:79], v[132:135], v[200:203], v[76:79]
	v_mfma_f32_16x16x32_bf16 v[72:75], v[140:143], v[200:203], v[72:75]
	s_barrier
	s_add_i32 s29, 0, 0x1c000
	s_add_i32 s28, s28, s47
	s_add_i32 m0, s28, 0xffffff80
	s_nop 0
	global_load_lds_dwordx4 v176, s[68:69] offset:128
	s_add_i32 m0, s28, 0x1f80
	s_nop 0
	global_load_lds_dwordx4 v156, s[68:69] offset:128
	ds_read_b128 v[204:207], v174 offset:49152
	ds_read_b128 v[208:211], v174 offset:50176
	ds_read_b128 v[212:215], v174 offset:51200
	ds_read_b128 v[232:235], v174 offset:52224
	s_barrier
	s_waitcnt lgkmcnt(3)
	v_mfma_f32_16x16x32_bf16 v[116:119], v[204:207], v[144:147], v[116:119]
	s_waitcnt lgkmcnt(1)
	v_mfma_f32_16x16x32_bf16 v[112:115], v[212:215], v[144:147], v[112:115]
	v_mfma_f32_16x16x32_bf16 v[100:103], v[204:207], v[162:165], v[100:103]
	v_mfma_f32_16x16x32_bf16 v[96:99], v[212:215], v[162:165], v[96:99]
	v_mfma_f32_16x16x32_bf16 v[84:87], v[204:207], v[170:173], v[84:87]
	v_mfma_f32_16x16x32_bf16 v[80:83], v[212:215], v[170:173], v[80:83]
	v_mfma_f32_16x16x32_bf16 v[68:71], v[204:207], v[196:199], v[68:71]
	v_mfma_f32_16x16x32_bf16 v[64:67], v[212:215], v[196:199], v[64:67]
	v_mfma_f32_16x16x32_bf16 v[116:119], v[208:211], v[148:151], v[116:119]
	s_waitcnt lgkmcnt(0)
	v_mfma_f32_16x16x32_bf16 v[112:115], v[232:235], v[148:151], v[112:115]
	v_mfma_f32_16x16x32_bf16 v[100:103], v[208:211], v[166:169], v[100:103]
	v_mfma_f32_16x16x32_bf16 v[96:99], v[232:235], v[166:169], v[96:99]
	v_mfma_f32_16x16x32_bf16 v[84:87], v[208:211], v[188:191], v[84:87]
	v_mfma_f32_16x16x32_bf16 v[80:83], v[232:235], v[188:191], v[80:83]
	v_mfma_f32_16x16x32_bf16 v[68:71], v[208:211], v[200:203], v[68:71]
	v_mfma_f32_16x16x32_bf16 v[64:67], v[232:235], v[200:203], v[64:67]
	s_add_i32 m0, s74, 0xffffff80
	s_barrier
	global_load_lds_dwordx4 v152, s[66:67] offset:128
	s_add_i32 m0, s75, 0xffffff80
	s_nop 0
	global_load_lds_dwordx4 v154, s[66:67] offset:128
	ds_read_b128 v[144:147], v195 offset:49152
	ds_read_b128 v[162:165], v195 offset:51200
	ds_read_b128 v[170:173], v195 offset:53248
	ds_read_b128 v[196:199], v195 offset:55296
	ds_read_b128 v[148:151], v195 offset:50176
	ds_read_b128 v[166:169], v195 offset:52224
	ds_read_b128 v[188:191], v195 offset:54272
	ds_read_b128 v[200:203], v195 offset:56320
	s_barrier
	s_waitcnt lgkmcnt(7)
	v_mfma_f32_16x16x32_bf16 v[60:63], v[128:131], v[144:147], v[60:63]
	v_mfma_f32_16x16x32_bf16 v[56:59], v[136:139], v[144:147], v[56:59]
	s_waitcnt lgkmcnt(6)
	v_mfma_f32_16x16x32_bf16 v[44:47], v[128:131], v[162:165], v[44:47]
	v_mfma_f32_16x16x32_bf16 v[40:43], v[136:139], v[162:165], v[40:43]
	s_waitcnt lgkmcnt(5)
	v_mfma_f32_16x16x32_bf16 v[28:31], v[128:131], v[170:173], v[28:31]
	v_mfma_f32_16x16x32_bf16 v[24:27], v[136:139], v[170:173], v[24:27]
	s_waitcnt lgkmcnt(4)
	v_mfma_f32_16x16x32_bf16 v[12:15], v[128:131], v[196:199], v[12:15]
	v_mfma_f32_16x16x32_bf16 v[8:11], v[136:139], v[196:199], v[8:11]
	s_waitcnt lgkmcnt(3)
	v_mfma_f32_16x16x32_bf16 v[60:63], v[132:135], v[148:151], v[60:63]
	v_mfma_f32_16x16x32_bf16 v[56:59], v[140:143], v[148:151], v[56:59]
	s_waitcnt lgkmcnt(2)
	v_mfma_f32_16x16x32_bf16 v[44:47], v[132:135], v[166:169], v[44:47]
	v_mfma_f32_16x16x32_bf16 v[40:43], v[140:143], v[166:169], v[40:43]
	s_waitcnt lgkmcnt(1)
	v_mfma_f32_16x16x32_bf16 v[28:31], v[132:135], v[188:191], v[28:31]
	v_mfma_f32_16x16x32_bf16 v[24:27], v[140:143], v[188:191], v[24:27]
	s_waitcnt lgkmcnt(0)
	v_mfma_f32_16x16x32_bf16 v[12:15], v[132:135], v[200:203], v[12:15]
	v_mfma_f32_16x16x32_bf16 v[8:11], v[140:143], v[200:203], v[8:11]
	s_barrier
	s_add_i32 s28, s29, s47
	s_add_i32 m0, s28, 0xffffff80
	s_nop 0
	global_load_lds_dwordx4 v176, s[98:99] offset:128
	s_add_i32 m0, s28, 0x1f80
	s_nop 0
	global_load_lds_dwordx4 v156, s[98:99] offset:128
	s_waitcnt vmcnt(6)
	s_barrier
	v_mfma_f32_16x16x32_bf16 v[52:55], v[204:207], v[144:147], v[52:55]
	v_mfma_f32_16x16x32_bf16 v[48:51], v[212:215], v[144:147], v[48:51]
	v_mfma_f32_16x16x32_bf16 v[36:39], v[204:207], v[162:165], v[36:39]
	v_mfma_f32_16x16x32_bf16 v[32:35], v[212:215], v[162:165], v[32:35]
	v_mfma_f32_16x16x32_bf16 v[20:23], v[204:207], v[170:173], v[20:23]
	v_mfma_f32_16x16x32_bf16 v[16:19], v[212:215], v[170:173], v[16:19]
	v_mfma_f32_16x16x32_bf16 v[4:7], v[204:207], v[196:199], v[4:7]
	v_mfma_f32_16x16x32_bf16 v[0:3], v[212:215], v[196:199], v[0:3]
	v_mfma_f32_16x16x32_bf16 v[52:55], v[208:211], v[148:151], v[52:55]
	v_mfma_f32_16x16x32_bf16 v[48:51], v[232:235], v[148:151], v[48:51]
	v_mfma_f32_16x16x32_bf16 v[36:39], v[208:211], v[166:169], v[36:39]
	v_mfma_f32_16x16x32_bf16 v[32:35], v[232:235], v[166:169], v[32:35]
	v_mfma_f32_16x16x32_bf16 v[20:23], v[208:211], v[188:191], v[20:23]
	v_mfma_f32_16x16x32_bf16 v[16:19], v[232:235], v[188:191], v[16:19]
	v_mfma_f32_16x16x32_bf16 v[4:7], v[208:211], v[200:203], v[4:7]
	v_mfma_f32_16x16x32_bf16 v[0:3], v[232:235], v[200:203], v[0:3]
	s_add_u32 s64, s64, 0x100
	s_addc_u32 s65, s65, 0
	s_add_u32 s91, s91, 0x100
	s_addc_u32 vcc_lo, vcc_lo, 0
	s_cmp_lt_i32 vcc_hi, s76
	s_mov_b32 s66, vcc_hi
	s_barrier
	s_cbranch_scc1 .LBB0_1114
	s_lshl_b32 s28, s84, 8
	v_mov_b32_e32 v128, v193
	v_mov_b32_e32 v129, v192
	s_add_i32 s28, s28, s78
	s_lshl_b32 s64, s24, 2
	v_add_u32_e32 v166, s28, v129
	s_lshl_b32 s28, s24, 8
	s_or_b32 s28, s28, s79
	v_lshl_add_u32 v162, v128, 3, s28
	v_ashrrev_i32_e32 v163, 31, v162
	v_lshlrev_b64 v[204:205], 1, v[162:163]
	v_ashrrev_i32_e32 v167, 31, v166
	v_lshl_add_u64 v[164:165], s[12:13], 0, v[204:205]
	v_lshlrev_b64 v[206:207], 11, v[166:167]
	v_cmp_eq_u32_e32 vcc, 0, v128
	v_lshl_add_u64 v[128:129], v[164:165], 0, v[206:207]
	global_load_dwordx4 v[196:199], v[128:129], off
	global_load_dwordx4 v[200:203], v[128:129], off offset:256
	v_add_u32_e32 v188, 16, v166
	v_ashrrev_i32_e32 v189, 31, v188
	v_add_u32_e32 v172, 32, v166
	v_lshlrev_b64 v[190:191], 11, v[188:189]
	v_ashrrev_i32_e32 v173, 31, v172
	v_add_u32_e32 v168, 48, v166
	v_lshl_add_u64 v[128:129], v[164:165], 0, v[190:191]
	v_lshlrev_b64 v[174:175], 11, v[172:173]
	v_ashrrev_i32_e32 v169, 31, v168
	global_load_dwordx4 v[148:151], v[128:129], off
	global_load_dwordx4 v[144:147], v[128:129], off offset:256
	v_lshl_add_u64 v[128:129], v[164:165], 0, v[174:175]
	v_lshlrev_b64 v[170:171], 11, v[168:169]
	global_load_dwordx4 v[140:143], v[128:129], off
	global_load_dwordx4 v[136:139], v[128:129], off offset:256
	v_lshl_add_u64 v[128:129], v[164:165], 0, v[170:171]
	global_load_dwordx4 v[132:135], v[128:129], off
	s_nop 0
	global_load_dwordx4 v[128:131], v[128:129], off offset:256
	v_lshl_add_u64 v[206:207], s[12:13], 0, v[206:207]
	v_lshl_add_u64 v[204:205], v[206:207], 0, v[204:205]
	s_ashr_i32 s65, s64, 31
	s_waitcnt vmcnt(0)
	v_lshlrev_b32_e32 v208, 16, v196
	v_and_b32_e32 v209, 0xffff0000, v196
	v_lshlrev_b32_e32 v196, 16, v197
	v_and_b32_e32 v197, 0xffff0000, v197
	v_lshlrev_b32_e32 v210, 16, v198
	v_and_b32_e32 v211, 0xffff0000, v198
	v_lshlrev_b32_e32 v198, 16, v199
	v_and_b32_e32 v199, 0xffff0000, v199
	v_pk_fma_f32 v[126:127], s[62:63], v[126:127], v[196:197]
	v_pk_fma_f32 v[124:125], s[10:11], v[124:125], v[208:209]
	v_pk_fma_f32 v[196:197], s[62:63], v[122:123], v[198:199]
	v_pk_fma_f32 v[198:199], s[10:11], v[120:121], v[210:211]
	v_cvt_pk_bf16_f32 v120, v124, v125
	v_cvt_pk_bf16_f32 v121, v126, v127
	s_nop 0
	v_cvt_pk_bf16_f32 v122, v198, v199
	v_cvt_pk_bf16_f32 v123, v196, v197
	global_store_dwordx4 v[204:205], v[120:123], off
	s_nop 1
	v_pk_mul_f32 v[120:121], v[198:199], v[198:199]
	v_pk_mul_f32 v[122:123], v[196:197], v[196:197]
	v_pk_fma_f32 v[120:121], v[124:125], v[124:125], v[120:121]
	v_pk_fma_f32 v[122:123], v[126:127], v[126:127], v[122:123]
	v_add_f32_e32 v120, v120, v121
	v_add_f32_e32 v121, v122, v123
	v_add_f32_e32 v196, v120, v121
	v_lshlrev_b32_e32 v120, 16, v200
	v_and_b32_e32 v121, 0xffff0000, v200
	v_lshlrev_b32_e32 v122, 16, v201
	v_and_b32_e32 v123, 0xffff0000, v201
	v_lshlrev_b32_e32 v124, 16, v202
	v_and_b32_e32 v125, 0xffff0000, v202
	v_lshlrev_b32_e32 v126, 16, v203
	v_and_b32_e32 v127, 0xffff0000, v203
	v_pk_fma_f32 v[118:119], s[62:63], v[118:119], v[122:123]
	v_pk_fma_f32 v[116:117], s[10:11], v[116:117], v[120:121]
	v_pk_fma_f32 v[120:121], s[62:63], v[114:115], v[126:127]
	v_pk_fma_f32 v[122:123], s[10:11], v[112:113], v[124:125]
	v_cvt_pk_bf16_f32 v112, v116, v117
	v_cvt_pk_bf16_f32 v113, v118, v119
	s_nop 0
	v_cvt_pk_bf16_f32 v114, v122, v123
	v_cvt_pk_bf16_f32 v115, v120, v121
	global_store_dwordx4 v[204:205], v[112:115], off offset:256
	s_nop 1
	v_pk_mul_f32 v[112:113], v[122:123], v[122:123]
	v_pk_mul_f32 v[114:115], v[120:121], v[120:121]
	v_pk_fma_f32 v[112:113], v[116:117], v[116:117], v[112:113]
	v_pk_fma_f32 v[114:115], v[118:119], v[118:119], v[114:115]
	v_add_f32_e32 v112, v112, v113
	v_add_f32_e32 v113, v114, v115
	v_add_f32_e32 v112, v112, v113
	v_add_f32_e32 v112, v196, v112
	ds_bpermute_b32 v113, v219, v112
	s_waitcnt lgkmcnt(0)
	v_add_f32_e32 v112, v112, v113
	ds_bpermute_b32 v113, v218, v112
	s_and_saveexec_b64 s[66:67], vcc
	s_cbranch_execz .LBB0_1117
	v_lshlrev_b64 v[114:115], 6, v[166:167]
	v_lshl_add_u64 v[114:115], s[8:9], 0, v[114:115]
	v_lshl_add_u64 v[114:115], s[64:65], 2, v[114:115]
	s_lshl_b32 s24, s77, 2
	v_lshl_add_u64 v[114:115], v[114:115], 0, s[24:25]
	s_waitcnt lgkmcnt(0)
	v_add_f32_e32 v112, v112, v113
	global_store_dword v[114:115], v112, off

.LBB0_1282:
	s_add_i32 s81, s60, 2
	s_add_u32 s28, s58, 0x80
	s_addc_u32 s29, s59, 0
	s_add_i32 s82, 0, 0x10000
	s_cmp_eq_u32 s5, s60
	s_cselect_b32 s60, s56, s28
	s_cselect_b32 s61, s57, s29
	s_cselect_b32 s63, s3, s80
	s_cselect_b32 s62, s2, s21
	s_add_i32 m0, s66, 0xc000
	s_nop 0
	global_load_lds_dwordx4 v158, s[58:59]
	s_add_i32 m0, s66, 0xe000
	s_nop 0
	global_load_lds_dwordx4 v160, s[58:59]
	ds_read_b128 v[128:131], v174
	ds_read_b128 v[132:135], v174 offset:1024
	ds_read_b128 v[136:139], v174 offset:2048
	ds_read_b128 v[140:143], v174 offset:3072
	ds_read_b128 v[144:147], v196
	ds_read_b128 v[162:165], v196 offset:2048
	ds_read_b128 v[170:173], v196 offset:4096
	ds_read_b128 v[198:201], v196 offset:6144
	ds_read_b128 v[148:151], v196 offset:1024
	ds_read_b128 v[166:169], v196 offset:3072
	ds_read_b128 v[188:191], v196 offset:5120
	ds_read_b128 v[202:205], v196 offset:7168
	s_waitcnt lgkmcnt(8)
	s_barrier
	s_waitcnt lgkmcnt(7)
	v_mfma_f32_16x16x32_bf16 v[124:127], v[128:131], v[144:147], v[124:127]
	v_mfma_f32_16x16x32_bf16 v[120:123], v[136:139], v[144:147], v[120:123]
	s_waitcnt lgkmcnt(6)
	v_mfma_f32_16x16x32_bf16 v[108:111], v[128:131], v[162:165], v[108:111]
	v_mfma_f32_16x16x32_bf16 v[104:107], v[136:139], v[162:165], v[104:107]
	s_waitcnt lgkmcnt(5)
	v_mfma_f32_16x16x32_bf16 v[92:95], v[128:131], v[170:173], v[92:95]
	v_mfma_f32_16x16x32_bf16 v[88:91], v[136:139], v[170:173], v[88:91]
	s_waitcnt lgkmcnt(4)
	v_mfma_f32_16x16x32_bf16 v[76:79], v[128:131], v[198:201], v[76:79]
	v_mfma_f32_16x16x32_bf16 v[72:75], v[136:139], v[198:201], v[72:75]
	s_waitcnt lgkmcnt(3)
	v_mfma_f32_16x16x32_bf16 v[124:127], v[132:135], v[148:151], v[124:127]
	v_mfma_f32_16x16x32_bf16 v[120:123], v[140:143], v[148:151], v[120:123]
	s_waitcnt lgkmcnt(2)
	v_mfma_f32_16x16x32_bf16 v[108:111], v[132:135], v[166:169], v[108:111]
	v_mfma_f32_16x16x32_bf16 v[104:107], v[140:143], v[166:169], v[104:107]
	s_waitcnt lgkmcnt(1)
	v_mfma_f32_16x16x32_bf16 v[92:95], v[132:135], v[188:191], v[92:95]
	v_mfma_f32_16x16x32_bf16 v[88:91], v[140:143], v[188:191], v[88:91]
	s_waitcnt lgkmcnt(0)
	v_mfma_f32_16x16x32_bf16 v[76:79], v[132:135], v[202:205], v[76:79]
	v_mfma_f32_16x16x32_bf16 v[72:75], v[140:143], v[202:205], v[72:75]
	s_barrier
	s_add_i32 s28, 0, 0x14000
	s_add_i32 s29, s82, s65
	s_mov_b32 m0, s29
	s_nop 0
	global_load_lds_dwordx4 v176, s[62:63]
	s_add_i32 m0, s29, 0x2000
	s_nop 0
	global_load_lds_dwordx4 v156, s[62:63]
	ds_read_b128 v[206:209], v174 offset:16384
	ds_read_b128 v[210:213], v174 offset:17408
	ds_read_b128 v[214:217], v174 offset:18432
	ds_read_b128 v[232:235], v174 offset:19456
	s_barrier
	s_waitcnt lgkmcnt(3)
	v_mfma_f32_16x16x32_bf16 v[116:119], v[206:209], v[144:147], v[116:119]
	s_waitcnt lgkmcnt(1)
	v_mfma_f32_16x16x32_bf16 v[112:115], v[214:217], v[144:147], v[112:115]
	v_mfma_f32_16x16x32_bf16 v[100:103], v[206:209], v[162:165], v[100:103]
	v_mfma_f32_16x16x32_bf16 v[96:99], v[214:217], v[162:165], v[96:99]
	v_mfma_f32_16x16x32_bf16 v[84:87], v[206:209], v[170:173], v[84:87]
	v_mfma_f32_16x16x32_bf16 v[80:83], v[214:217], v[170:173], v[80:83]
	v_mfma_f32_16x16x32_bf16 v[68:71], v[206:209], v[198:201], v[68:71]
	v_mfma_f32_16x16x32_bf16 v[64:67], v[214:217], v[198:201], v[64:67]
	v_mfma_f32_16x16x32_bf16 v[116:119], v[210:213], v[148:151], v[116:119]
	s_waitcnt lgkmcnt(0)
	v_mfma_f32_16x16x32_bf16 v[112:115], v[232:235], v[148:151], v[112:115]
	v_mfma_f32_16x16x32_bf16 v[100:103], v[210:213], v[166:169], v[100:103]
	v_mfma_f32_16x16x32_bf16 v[96:99], v[232:235], v[166:169], v[96:99]
	v_mfma_f32_16x16x32_bf16 v[84:87], v[210:213], v[188:191], v[84:87]
	v_mfma_f32_16x16x32_bf16 v[80:83], v[232:235], v[188:191], v[80:83]
	v_mfma_f32_16x16x32_bf16 v[68:71], v[210:213], v[202:205], v[68:71]
	v_mfma_f32_16x16x32_bf16 v[64:67], v[232:235], v[202:205], v[64:67]
	s_mov_b32 m0, s66
	s_barrier
	global_load_lds_dwordx4 v152, s[60:61]
	s_mov_b32 m0, s67
	s_nop 0
	global_load_lds_dwordx4 v154, s[60:61]
	ds_read_b128 v[144:147], v196 offset:16384
	ds_read_b128 v[162:165], v196 offset:18432
	ds_read_b128 v[170:173], v196 offset:20480
	ds_read_b128 v[198:201], v196 offset:22528
	ds_read_b128 v[148:151], v196 offset:17408
	ds_read_b128 v[166:169], v196 offset:19456
	ds_read_b128 v[188:191], v196 offset:21504
	ds_read_b128 v[202:205], v196 offset:23552
	s_barrier
	s_waitcnt lgkmcnt(7)
	v_mfma_f32_16x16x32_bf16 v[60:63], v[128:131], v[144:147], v[60:63]
	v_mfma_f32_16x16x32_bf16 v[56:59], v[136:139], v[144:147], v[56:59]
	s_waitcnt lgkmcnt(6)
	v_mfma_f32_16x16x32_bf16 v[44:47], v[128:131], v[162:165], v[44:47]
	v_mfma_f32_16x16x32_bf16 v[40:43], v[136:139], v[162:165], v[40:43]
	s_waitcnt lgkmcnt(5)
	v_mfma_f32_16x16x32_bf16 v[28:31], v[128:131], v[170:173], v[28:31]
	v_mfma_f32_16x16x32_bf16 v[24:27], v[136:139], v[170:173], v[24:27]
	s_waitcnt lgkmcnt(4)
	v_mfma_f32_16x16x32_bf16 v[12:15], v[128:131], v[198:201], v[12:15]
	v_mfma_f32_16x16x32_bf16 v[8:11], v[136:139], v[198:201], v[8:11]
	s_waitcnt lgkmcnt(3)
	v_mfma_f32_16x16x32_bf16 v[60:63], v[132:135], v[148:151], v[60:63]
	v_mfma_f32_16x16x32_bf16 v[56:59], v[140:143], v[148:151], v[56:59]
	s_waitcnt lgkmcnt(2)
	v_mfma_f32_16x16x32_bf16 v[44:47], v[132:135], v[166:169], v[44:47]
	v_mfma_f32_16x16x32_bf16 v[40:43], v[140:143], v[166:169], v[40:43]
	s_waitcnt lgkmcnt(1)
	v_mfma_f32_16x16x32_bf16 v[28:31], v[132:135], v[188:191], v[28:31]
	v_mfma_f32_16x16x32_bf16 v[24:27], v[140:143], v[188:191], v[24:27]
	s_waitcnt lgkmcnt(0)
	v_mfma_f32_16x16x32_bf16 v[12:15], v[132:135], v[202:205], v[12:15]
	v_mfma_f32_16x16x32_bf16 v[8:11], v[140:143], v[202:205], v[8:11]
	s_barrier
	s_add_u32 s98, s62, s4
	s_addc_u32 s99, s63, 0
	s_add_i32 s28, s28, s65
	s_mov_b32 m0, s28
	s_nop 0
	global_load_lds_dwordx4 v176, s[98:99]
	s_add_i32 m0, s28, 0x2000
	s_nop 0
	global_load_lds_dwordx4 v156, s[98:99]
	s_waitcnt vmcnt(6)
	s_barrier
	v_mfma_f32_16x16x32_bf16 v[52:55], v[206:209], v[144:147], v[52:55]
	v_mfma_f32_16x16x32_bf16 v[48:51], v[214:217], v[144:147], v[48:51]
	v_mfma_f32_16x16x32_bf16 v[36:39], v[206:209], v[162:165], v[36:39]
	v_mfma_f32_16x16x32_bf16 v[32:35], v[214:217], v[162:165], v[32:35]
	v_mfma_f32_16x16x32_bf16 v[20:23], v[206:209], v[170:173], v[20:23]
	v_mfma_f32_16x16x32_bf16 v[16:19], v[214:217], v[170:173], v[16:19]
	v_mfma_f32_16x16x32_bf16 v[4:7], v[206:209], v[198:201], v[4:7]
	v_mfma_f32_16x16x32_bf16 v[0:3], v[214:217], v[198:201], v[0:3]
	v_mfma_f32_16x16x32_bf16 v[52:55], v[210:213], v[148:151], v[52:55]
	v_mfma_f32_16x16x32_bf16 v[48:51], v[232:235], v[148:151], v[48:51]
	v_mfma_f32_16x16x32_bf16 v[36:39], v[210:213], v[166:169], v[36:39]
	v_mfma_f32_16x16x32_bf16 v[32:35], v[232:235], v[166:169], v[32:35]
	v_mfma_f32_16x16x32_bf16 v[20:23], v[210:213], v[188:191], v[20:23]
	v_mfma_f32_16x16x32_bf16 v[16:19], v[232:235], v[188:191], v[16:19]
	v_mfma_f32_16x16x32_bf16 v[4:7], v[210:213], v[202:205], v[4:7]
	v_mfma_f32_16x16x32_bf16 v[0:3], v[232:235], v[202:205], v[0:3]
	s_add_i32 s28, 0, 0x18000
	s_barrier
	s_add_u32 s100, s60, s4
	s_addc_u32 s101, s61, 0
	s_mov_b32 m0, s68
	s_nop 0
	global_load_lds_dwordx4 v152, s[100:101]
	s_mov_b32 m0, s69
	s_nop 0
	global_load_lds_dwordx4 v154, s[100:101]
	ds_read_b128 v[128:131], v174 offset:32768
	ds_read_b128 v[132:135], v174 offset:33792
	ds_read_b128 v[136:139], v174 offset:34816
	ds_read_b128 v[140:143], v174 offset:35840
	ds_read_b128 v[144:147], v196 offset:32768
	ds_read_b128 v[162:165], v196 offset:34816
	ds_read_b128 v[170:173], v196 offset:36864
	ds_read_b128 v[198:201], v196 offset:38912
	ds_read_b128 v[148:151], v196 offset:33792
	ds_read_b128 v[166:169], v196 offset:35840
	ds_read_b128 v[188:191], v196 offset:37888
	ds_read_b128 v[202:205], v196 offset:39936
	s_waitcnt lgkmcnt(8)
	s_barrier
	s_waitcnt lgkmcnt(7)
	v_mfma_f32_16x16x32_bf16 v[124:127], v[128:131], v[144:147], v[124:127]
	v_mfma_f32_16x16x32_bf16 v[120:123], v[136:139], v[144:147], v[120:123]
	s_waitcnt lgkmcnt(6)
	v_mfma_f32_16x16x32_bf16 v[108:111], v[128:131], v[162:165], v[108:111]
	v_mfma_f32_16x16x32_bf16 v[104:107], v[136:139], v[162:165], v[104:107]
	s_waitcnt lgkmcnt(5)
	v_mfma_f32_16x16x32_bf16 v[92:95], v[128:131], v[170:173], v[92:95]
	v_mfma_f32_16x16x32_bf16 v[88:91], v[136:139], v[170:173], v[88:91]
	s_waitcnt lgkmcnt(4)
	v_mfma_f32_16x16x32_bf16 v[76:79], v[128:131], v[198:201], v[76:79]
	v_mfma_f32_16x16x32_bf16 v[72:75], v[136:139], v[198:201], v[72:75]
	s_waitcnt lgkmcnt(3)
	v_mfma_f32_16x16x32_bf16 v[124:127], v[132:135], v[148:151], v[124:127]
	v_mfma_f32_16x16x32_bf16 v[120:123], v[140:143], v[148:151], v[120:123]
	s_waitcnt lgkmcnt(2)
	v_mfma_f32_16x16x32_bf16 v[108:111], v[132:135], v[166:169], v[108:111]
	v_mfma_f32_16x16x32_bf16 v[104:107], v[140:143], v[166:169], v[104:107]
	s_waitcnt lgkmcnt(1)
	v_mfma_f32_16x16x32_bf16 v[92:95], v[132:135], v[188:191], v[92:95]
	v_mfma_f32_16x16x32_bf16 v[88:91], v[140:143], v[188:191], v[88:91]
	s_waitcnt lgkmcnt(0)
	v_mfma_f32_16x16x32_bf16 v[76:79], v[132:135], v[202:205], v[76:79]
	v_mfma_f32_16x16x32_bf16 v[72:75], v[140:143], v[202:205], v[72:75]
	s_barrier
	s_add_i32 s29, 0, 0x1c000
	s_add_i32 s28, s28, s65
	s_add_i32 m0, s28, 0xffffff80
	s_nop 0
	global_load_lds_dwordx4 v176, s[62:63] offset:128
	s_add_i32 m0, s28, 0x1f80
	s_nop 0
	global_load_lds_dwordx4 v156, s[62:63] offset:128
	ds_read_b128 v[206:209], v174 offset:49152
	ds_read_b128 v[210:213], v174 offset:50176
	ds_read_b128 v[214:217], v174 offset:51200
	ds_read_b128 v[232:235], v174 offset:52224
	s_barrier
	s_waitcnt lgkmcnt(3)
	v_mfma_f32_16x16x32_bf16 v[116:119], v[206:209], v[144:147], v[116:119]
	s_waitcnt lgkmcnt(1)
	v_mfma_f32_16x16x32_bf16 v[112:115], v[214:217], v[144:147], v[112:115]
	v_mfma_f32_16x16x32_bf16 v[100:103], v[206:209], v[162:165], v[100:103]
	v_mfma_f32_16x16x32_bf16 v[96:99], v[214:217], v[162:165], v[96:99]
	v_mfma_f32_16x16x32_bf16 v[84:87], v[206:209], v[170:173], v[84:87]
	v_mfma_f32_16x16x32_bf16 v[80:83], v[214:217], v[170:173], v[80:83]
	v_mfma_f32_16x16x32_bf16 v[68:71], v[206:209], v[198:201], v[68:71]
	v_mfma_f32_16x16x32_bf16 v[64:67], v[214:217], v[198:201], v[64:67]
	v_mfma_f32_16x16x32_bf16 v[116:119], v[210:213], v[148:151], v[116:119]
	s_waitcnt lgkmcnt(0)
	v_mfma_f32_16x16x32_bf16 v[112:115], v[232:235], v[148:151], v[112:115]
	v_mfma_f32_16x16x32_bf16 v[100:103], v[210:213], v[166:169], v[100:103]
	v_mfma_f32_16x16x32_bf16 v[96:99], v[232:235], v[166:169], v[96:99]
	v_mfma_f32_16x16x32_bf16 v[84:87], v[210:213], v[188:191], v[84:87]
	v_mfma_f32_16x16x32_bf16 v[80:83], v[232:235], v[188:191], v[80:83]
	v_mfma_f32_16x16x32_bf16 v[68:71], v[210:213], v[202:205], v[68:71]
	v_mfma_f32_16x16x32_bf16 v[64:67], v[232:235], v[202:205], v[64:67]
	s_add_i32 m0, s71, 0xffffff80
	s_barrier
	global_load_lds_dwordx4 v152, s[60:61] offset:128
	s_add_i32 m0, s72, 0xffffff80
	s_nop 0
	global_load_lds_dwordx4 v154, s[60:61] offset:128
	ds_read_b128 v[144:147], v196 offset:49152
	ds_read_b128 v[162:165], v196 offset:51200
	ds_read_b128 v[170:173], v196 offset:53248
	ds_read_b128 v[198:201], v196 offset:55296
	ds_read_b128 v[148:151], v196 offset:50176
	ds_read_b128 v[166:169], v196 offset:52224
	ds_read_b128 v[188:191], v196 offset:54272
	ds_read_b128 v[202:205], v196 offset:56320
	s_barrier
	s_waitcnt lgkmcnt(7)
	v_mfma_f32_16x16x32_bf16 v[60:63], v[128:131], v[144:147], v[60:63]
	v_mfma_f32_16x16x32_bf16 v[56:59], v[136:139], v[144:147], v[56:59]
	s_waitcnt lgkmcnt(6)
	v_mfma_f32_16x16x32_bf16 v[44:47], v[128:131], v[162:165], v[44:47]
	v_mfma_f32_16x16x32_bf16 v[40:43], v[136:139], v[162:165], v[40:43]
	s_waitcnt lgkmcnt(5)
	v_mfma_f32_16x16x32_bf16 v[28:31], v[128:131], v[170:173], v[28:31]
	v_mfma_f32_16x16x32_bf16 v[24:27], v[136:139], v[170:173], v[24:27]
	s_waitcnt lgkmcnt(4)
	v_mfma_f32_16x16x32_bf16 v[12:15], v[128:131], v[198:201], v[12:15]
	v_mfma_f32_16x16x32_bf16 v[8:11], v[136:139], v[198:201], v[8:11]
	s_waitcnt lgkmcnt(3)
	v_mfma_f32_16x16x32_bf16 v[60:63], v[132:135], v[148:151], v[60:63]
	v_mfma_f32_16x16x32_bf16 v[56:59], v[140:143], v[148:151], v[56:59]
	s_waitcnt lgkmcnt(2)
	v_mfma_f32_16x16x32_bf16 v[44:47], v[132:135], v[166:169], v[44:47]
	v_mfma_f32_16x16x32_bf16 v[40:43], v[140:143], v[166:169], v[40:43]
	s_waitcnt lgkmcnt(1)
	v_mfma_f32_16x16x32_bf16 v[28:31], v[132:135], v[188:191], v[28:31]
	v_mfma_f32_16x16x32_bf16 v[24:27], v[140:143], v[188:191], v[24:27]
	s_waitcnt lgkmcnt(0)
	v_mfma_f32_16x16x32_bf16 v[12:15], v[132:135], v[202:205], v[12:15]
	v_mfma_f32_16x16x32_bf16 v[8:11], v[140:143], v[202:205], v[8:11]
	s_barrier
	s_add_i32 s28, s29, s65
	s_add_i32 m0, s28, 0xffffff80
	s_nop 0
	global_load_lds_dwordx4 v176, s[98:99] offset:128
	s_add_i32 m0, s28, 0x1f80
	s_nop 0
	global_load_lds_dwordx4 v156, s[98:99] offset:128
	s_waitcnt vmcnt(6)
	s_barrier
	v_mfma_f32_16x16x32_bf16 v[52:55], v[206:209], v[144:147], v[52:55]
	v_mfma_f32_16x16x32_bf16 v[48:51], v[214:217], v[144:147], v[48:51]
	v_mfma_f32_16x16x32_bf16 v[36:39], v[206:209], v[162:165], v[36:39]
	v_mfma_f32_16x16x32_bf16 v[32:35], v[214:217], v[162:165], v[32:35]
	v_mfma_f32_16x16x32_bf16 v[20:23], v[206:209], v[170:173], v[20:23]
	v_mfma_f32_16x16x32_bf16 v[16:19], v[214:217], v[170:173], v[16:19]
	v_mfma_f32_16x16x32_bf16 v[4:7], v[206:209], v[198:201], v[4:7]
	v_mfma_f32_16x16x32_bf16 v[0:3], v[214:217], v[198:201], v[0:3]
	v_mfma_f32_16x16x32_bf16 v[52:55], v[210:213], v[148:151], v[52:55]
	v_mfma_f32_16x16x32_bf16 v[48:51], v[232:235], v[148:151], v[48:51]
	v_mfma_f32_16x16x32_bf16 v[36:39], v[210:213], v[166:169], v[36:39]
	v_mfma_f32_16x16x32_bf16 v[32:35], v[232:235], v[166:169], v[32:35]
	v_mfma_f32_16x16x32_bf16 v[20:23], v[210:213], v[188:191], v[20:23]
	v_mfma_f32_16x16x32_bf16 v[16:19], v[232:235], v[188:191], v[16:19]
	v_mfma_f32_16x16x32_bf16 v[4:7], v[210:213], v[202:205], v[4:7]
	v_mfma_f32_16x16x32_bf16 v[0:3], v[232:235], v[202:205], v[0:3]
	s_add_u32 s58, s58, 0x100
	s_addc_u32 s59, s59, 0
	s_add_u32 s21, s21, 0x100
	s_addc_u32 s80, s80, 0
	s_cmp_ge_i32 s81, s79
	s_mov_b32 s60, s81
	s_barrier
	s_cbranch_scc0 .LBB0_1282
	s_cmp_gt_i32 s24, -1
	s_mov_b64 s[58:59], -1
	s_cbranch_scc0 .LBB0_1285
	s_lshl_b64 s[58:59], s[24:25], 17
	v_mov_b32_e32 v128, v231
	s_add_u32 s58, s37, s58
	s_addc_u32 s59, s46, s59
	v_ashrrev_i32_e32 v129, 31, v128
	v_lshl_add_u64 v[128:129], v[128:129], 4, s[58:59]
	v_add_co_u32_e32 v134, vcc, s36, v128
	v_cvt_pk_bf16_f32 v130, v124, v125
	v_cvt_pk_bf16_f32 v131, v126, v127
	v_cvt_pk_bf16_f32 v132, v120, v121
	v_cvt_pk_bf16_f32 v133, v122, v123
	s_nop 1
	v_addc_co_u32_e32 v135, vcc, 0, v129, vcc
	s_movk_i32 s5, 0x4000
	global_store_dwordx4 v[128:129], v[130:133], off
	s_mov_b64 s[58:59], 0
	s_nop 0
	v_cvt_pk_bf16_f32 v130, v108, v109
	v_cvt_pk_bf16_f32 v131, v110, v111
	v_cvt_pk_bf16_f32 v132, v104, v105
	v_cvt_pk_bf16_f32 v133, v106, v107
	global_store_dwordx4 v[134:135], v[130:133], off
	v_add_co_u32_e32 v134, vcc, s5, v128
	s_movk_i32 s5, 0x6000
	s_nop 0
	v_addc_co_u32_e32 v135, vcc, 0, v129, vcc
	v_cvt_pk_bf16_f32 v130, v92, v93
	v_cvt_pk_bf16_f32 v131, v94, v95
	v_cvt_pk_bf16_f32 v132, v88, v89
	v_cvt_pk_bf16_f32 v133, v90, v91
	global_store_dwordx4 v[134:135], v[130:133], off
	v_add_co_u32_e32 v134, vcc, s5, v128
	s_nop 0
	v_cvt_pk_bf16_f32 v130, v76, v77
	v_cvt_pk_bf16_f32 v131, v78, v79
	v_cvt_pk_bf16_f32 v132, v72, v73
	v_cvt_pk_bf16_f32 v133, v74, v75
	s_nop 0
	v_addc_co_u32_e32 v135, vcc, 0, v129, vcc
	global_store_dwordx4 v[134:135], v[130:133], off
	v_add_co_u32_e32 v134, vcc, s92, v128
	s_mov_b32 s5, 0xa000
	s_nop 0
	v_addc_co_u32_e32 v135, vcc, 0, v129, vcc
	v_cvt_pk_bf16_f32 v130, v116, v117
	v_cvt_pk_bf16_f32 v131, v118, v119
	v_cvt_pk_bf16_f32 v132, v112, v113
	v_cvt_pk_bf16_f32 v133, v114, v115
	global_store_dwordx4 v[134:135], v[130:133], off
	v_add_co_u32_e32 v134, vcc, s5, v128
	s_mov_b32 s5, 0xc000
	s_nop 0
	v_addc_co_u32_e32 v135, vcc, 0, v129, vcc
	v_cvt_pk_bf16_f32 v130, v100, v101
	v_cvt_pk_bf16_f32 v131, v102, v103
	v_cvt_pk_bf16_f32 v132, v96, v97
	v_cvt_pk_bf16_f32 v133, v98, v99
	global_store_dwordx4 v[134:135], v[130:133], off
	v_add_co_u32_e32 v134, vcc, s5, v128
	s_mov_b32 s5, 0xe000
	s_nop 0
	v_addc_co_u32_e32 v135, vcc, 0, v129, vcc
	v_cvt_pk_bf16_f32 v130, v84, v85
	v_cvt_pk_bf16_f32 v131, v86, v87
	v_cvt_pk_bf16_f32 v132, v80, v81
	v_cvt_pk_bf16_f32 v133, v82, v83
	global_store_dwordx4 v[134:135], v[130:133], off
	v_add_co_u32_e32 v134, vcc, s5, v128
	s_mov_b32 s5, 0x10000
	s_nop 0
	v_addc_co_u32_e32 v135, vcc, 0, v129, vcc
	v_cvt_pk_bf16_f32 v130, v68, v69
	v_cvt_pk_bf16_f32 v131, v70, v71
	v_cvt_pk_bf16_f32 v132, v64, v65
	v_cvt_pk_bf16_f32 v133, v66, v67
	global_store_dwordx4 v[134:135], v[130:133], off
	v_add_co_u32_e32 v134, vcc, s5, v128
	s_mov_b32 s5, 0x12000
	s_nop 0
	v_addc_co_u32_e32 v135, vcc, 0, v129, vcc
	v_cvt_pk_bf16_f32 v130, v60, v61
	v_cvt_pk_bf16_f32 v131, v62, v63
	v_cvt_pk_bf16_f32 v132, v56, v57
	v_cvt_pk_bf16_f32 v133, v58, v59
	global_store_dwordx4 v[134:135], v[130:133], off
	v_add_co_u32_e32 v134, vcc, s5, v128
	s_mov_b32 s5, 0x14000
	s_nop 0
	v_addc_co_u32_e32 v135, vcc, 0, v129, vcc
	v_cvt_pk_bf16_f32 v130, v44, v45
	v_cvt_pk_bf16_f32 v131, v46, v47
	v_cvt_pk_bf16_f32 v132, v40, v41
	v_cvt_pk_bf16_f32 v133, v42, v43
	global_store_dwordx4 v[134:135], v[130:133], off
	v_add_co_u32_e32 v134, vcc, s5, v128
	s_mov_b32 s5, 0x16000
	s_nop 0
	v_addc_co_u32_e32 v135, vcc, 0, v129, vcc
	v_cvt_pk_bf16_f32 v130, v28, v29
	v_cvt_pk_bf16_f32 v131, v30, v31
	v_cvt_pk_bf16_f32 v132, v24, v25
	v_cvt_pk_bf16_f32 v133, v26, v27
	global_store_dwordx4 v[134:135], v[130:133], off
	v_add_co_u32_e32 v134, vcc, s5, v128
	s_mov_b32 s5, 0x18000
	s_nop 0
	v_addc_co_u32_e32 v135, vcc, 0, v129, vcc
	v_cvt_pk_bf16_f32 v130, v12, v13
	v_cvt_pk_bf16_f32 v131, v14, v15
	v_cvt_pk_bf16_f32 v132, v8, v9
	v_cvt_pk_bf16_f32 v133, v10, v11
	global_store_dwordx4 v[134:135], v[130:133], off
	v_add_co_u32_e32 v134, vcc, s5, v128
	s_mov_b32 s5, 0x1a000
	s_nop 0
	v_addc_co_u32_e32 v135, vcc, 0, v129, vcc
	v_cvt_pk_bf16_f32 v130, v52, v53
	v_cvt_pk_bf16_f32 v131, v54, v55
	v_cvt_pk_bf16_f32 v132, v48, v49
	v_cvt_pk_bf16_f32 v133, v50, v51
	global_store_dwordx4 v[134:135], v[130:133], off
	v_add_co_u32_e32 v134, vcc, s5, v128
	s_mov_b32 s5, 0x1c000
	s_nop 0
	v_addc_co_u32_e32 v135, vcc, 0, v129, vcc
	v_cvt_pk_bf16_f32 v130, v36, v37
	v_cvt_pk_bf16_f32 v131, v38, v39
	v_cvt_pk_bf16_f32 v132, v32, v33
	v_cvt_pk_bf16_f32 v133, v34, v35
	global_store_dwordx4 v[134:135], v[130:133], off
	v_add_co_u32_e32 v134, vcc, s5, v128
	s_nop 0
	v_cvt_pk_bf16_f32 v130, v20, v21
	v_cvt_pk_bf16_f32 v131, v22, v23
	v_cvt_pk_bf16_f32 v132, v16, v17
	v_cvt_pk_bf16_f32 v133, v18, v19
	s_nop 0
	v_addc_co_u32_e32 v135, vcc, 0, v129, vcc
	v_add_co_u32_e32 v128, vcc, 0x1e000, v128
	global_store_dwordx4 v[134:135], v[130:133], off
	s_nop 0
	v_addc_co_u32_e32 v129, vcc, 0, v129, vcc
	v_cvt_pk_bf16_f32 v130, v4, v5
	v_cvt_pk_bf16_f32 v131, v6, v7
	v_cvt_pk_bf16_f32 v132, v0, v1
	v_cvt_pk_bf16_f32 v133, v2, v3
	global_store_dwordx4 v[128:129], v[130:133], off

.LBB0_1436:
	s_add_u32 s28, s6, 0xfffc0080
	s_addc_u32 s29, s7, -1
	s_add_i32 s71, 0, 0x10000
	s_cmp_eq_u32 s70, 12
	s_cselect_b32 s53, s17, s29
	s_cselect_b32 s52, s66, s28
	s_cselect_b32 s51, s13, s69
	s_cselect_b32 s50, s67, s68
	s_add_i32 m0, s56, 0xc000
	s_nop 0
	global_load_lds_dwordx4 v162, s[6:7]
	s_add_i32 m0, s56, 0xe000
	s_nop 0
	global_load_lds_dwordx4 v164, s[6:7]
	ds_read_b128 v[128:131], v174
	ds_read_b128 v[132:135], v174 offset:1024
	ds_read_b128 v[136:139], v174 offset:2048
	ds_read_b128 v[140:143], v174 offset:3072
	ds_read_b128 v[144:147], v201
	ds_read_b128 v[152:155], v201 offset:2048
	ds_read_b128 v[170:173], v201 offset:4096
	ds_read_b128 v[192:195], v201 offset:6144
	ds_read_b128 v[148:151], v201 offset:1024
	ds_read_b128 v[166:169], v201 offset:3072
	ds_read_b128 v[188:191], v201 offset:5120
	ds_read_b128 v[202:205], v201 offset:7168
	s_waitcnt lgkmcnt(8)
	s_barrier
	s_waitcnt lgkmcnt(7)
	v_mfma_f32_16x16x32_bf16 v[124:127], v[128:131], v[144:147], v[124:127]
	v_mfma_f32_16x16x32_bf16 v[116:119], v[136:139], v[144:147], v[116:119]
	s_waitcnt lgkmcnt(6)
	v_mfma_f32_16x16x32_bf16 v[108:111], v[128:131], v[152:155], v[108:111]
	v_mfma_f32_16x16x32_bf16 v[100:103], v[136:139], v[152:155], v[100:103]
	s_waitcnt lgkmcnt(5)
	v_mfma_f32_16x16x32_bf16 v[92:95], v[128:131], v[170:173], v[92:95]
	v_mfma_f32_16x16x32_bf16 v[84:87], v[136:139], v[170:173], v[84:87]
	s_waitcnt lgkmcnt(4)
	v_mfma_f32_16x16x32_bf16 v[76:79], v[128:131], v[192:195], v[76:79]
	v_mfma_f32_16x16x32_bf16 v[68:71], v[136:139], v[192:195], v[68:71]
	s_waitcnt lgkmcnt(3)
	v_mfma_f32_16x16x32_bf16 v[124:127], v[132:135], v[148:151], v[124:127]
	v_mfma_f32_16x16x32_bf16 v[116:119], v[140:143], v[148:151], v[116:119]
	s_waitcnt lgkmcnt(2)
	v_mfma_f32_16x16x32_bf16 v[108:111], v[132:135], v[166:169], v[108:111]
	v_mfma_f32_16x16x32_bf16 v[100:103], v[140:143], v[166:169], v[100:103]
	s_waitcnt lgkmcnt(1)
	v_mfma_f32_16x16x32_bf16 v[92:95], v[132:135], v[188:191], v[92:95]
	v_mfma_f32_16x16x32_bf16 v[84:87], v[140:143], v[188:191], v[84:87]
	s_waitcnt lgkmcnt(0)
	v_mfma_f32_16x16x32_bf16 v[76:79], v[132:135], v[202:205], v[76:79]
	v_mfma_f32_16x16x32_bf16 v[68:71], v[140:143], v[202:205], v[68:71]
	s_barrier
	s_add_i32 s28, 0, 0x14000
	s_add_i32 s29, s71, s55
	s_mov_b32 m0, s29
	s_nop 0
	global_load_lds_dwordx4 v176, s[50:51]
	s_add_i32 m0, s29, 0x2000
	s_nop 0
	global_load_lds_dwordx4 v160, s[50:51]
	ds_read_b128 v[206:209], v174 offset:16384
	ds_read_b128 v[210:213], v174 offset:17408
	ds_read_b128 v[214:217], v174 offset:18432
	ds_read_b128 v[232:235], v174 offset:19456
	s_barrier
	s_waitcnt lgkmcnt(3)
	v_mfma_f32_16x16x32_bf16 v[120:123], v[206:209], v[144:147], v[120:123]
	s_waitcnt lgkmcnt(1)
	v_mfma_f32_16x16x32_bf16 v[112:115], v[214:217], v[144:147], v[112:115]
	v_mfma_f32_16x16x32_bf16 v[104:107], v[206:209], v[152:155], v[104:107]
	v_mfma_f32_16x16x32_bf16 v[96:99], v[214:217], v[152:155], v[96:99]
	v_mfma_f32_16x16x32_bf16 v[88:91], v[206:209], v[170:173], v[88:91]
	v_mfma_f32_16x16x32_bf16 v[80:83], v[214:217], v[170:173], v[80:83]
	v_mfma_f32_16x16x32_bf16 v[72:75], v[206:209], v[192:195], v[72:75]
	v_mfma_f32_16x16x32_bf16 v[64:67], v[214:217], v[192:195], v[64:67]
	v_mfma_f32_16x16x32_bf16 v[120:123], v[210:213], v[148:151], v[120:123]
	s_waitcnt lgkmcnt(0)
	v_mfma_f32_16x16x32_bf16 v[112:115], v[232:235], v[148:151], v[112:115]
	v_mfma_f32_16x16x32_bf16 v[104:107], v[210:213], v[166:169], v[104:107]
	v_mfma_f32_16x16x32_bf16 v[96:99], v[232:235], v[166:169], v[96:99]
	v_mfma_f32_16x16x32_bf16 v[88:91], v[210:213], v[188:191], v[88:91]
	v_mfma_f32_16x16x32_bf16 v[80:83], v[232:235], v[188:191], v[80:83]
	v_mfma_f32_16x16x32_bf16 v[72:75], v[210:213], v[202:205], v[72:75]
	v_mfma_f32_16x16x32_bf16 v[64:67], v[232:235], v[202:205], v[64:67]
	s_mov_b32 m0, s56
	s_barrier
	global_load_lds_dwordx4 v156, s[52:53]
	s_mov_b32 m0, s57
	s_nop 0
	global_load_lds_dwordx4 v158, s[52:53]
	ds_read_b128 v[144:147], v201 offset:16384
	ds_read_b128 v[152:155], v201 offset:18432
	ds_read_b128 v[170:173], v201 offset:20480
	ds_read_b128 v[192:195], v201 offset:22528
	ds_read_b128 v[148:151], v201 offset:17408
	ds_read_b128 v[166:169], v201 offset:19456
	ds_read_b128 v[188:191], v201 offset:21504
	ds_read_b128 v[202:205], v201 offset:23552
	s_barrier
	s_waitcnt lgkmcnt(7)
	v_mfma_f32_16x16x32_bf16 v[60:63], v[128:131], v[144:147], v[60:63]
	v_mfma_f32_16x16x32_bf16 v[52:55], v[136:139], v[144:147], v[52:55]
	s_waitcnt lgkmcnt(6)
	v_mfma_f32_16x16x32_bf16 v[44:47], v[128:131], v[152:155], v[44:47]
	v_mfma_f32_16x16x32_bf16 v[36:39], v[136:139], v[152:155], v[36:39]
	s_waitcnt lgkmcnt(5)
	v_mfma_f32_16x16x32_bf16 v[28:31], v[128:131], v[170:173], v[28:31]
	v_mfma_f32_16x16x32_bf16 v[20:23], v[136:139], v[170:173], v[20:23]
	s_waitcnt lgkmcnt(4)
	v_mfma_f32_16x16x32_bf16 v[12:15], v[128:131], v[192:195], v[12:15]
	v_mfma_f32_16x16x32_bf16 v[4:7], v[136:139], v[192:195], v[4:7]
	s_waitcnt lgkmcnt(3)
	v_mfma_f32_16x16x32_bf16 v[60:63], v[132:135], v[148:151], v[60:63]
	v_mfma_f32_16x16x32_bf16 v[52:55], v[140:143], v[148:151], v[52:55]
	s_waitcnt lgkmcnt(2)
	v_mfma_f32_16x16x32_bf16 v[44:47], v[132:135], v[166:169], v[44:47]
	v_mfma_f32_16x16x32_bf16 v[36:39], v[140:143], v[166:169], v[36:39]
	s_waitcnt lgkmcnt(1)
	v_mfma_f32_16x16x32_bf16 v[28:31], v[132:135], v[188:191], v[28:31]
	v_mfma_f32_16x16x32_bf16 v[20:23], v[140:143], v[188:191], v[20:23]
	s_waitcnt lgkmcnt(0)
	v_mfma_f32_16x16x32_bf16 v[12:15], v[132:135], v[202:205], v[12:15]
	v_mfma_f32_16x16x32_bf16 v[4:7], v[140:143], v[202:205], v[4:7]
	s_barrier
	s_add_u32 s72, s50, 0x40000
	s_addc_u32 s73, s51, 0
	s_add_i32 s28, s28, s55
	s_mov_b32 m0, s28
	s_nop 0
	global_load_lds_dwordx4 v176, s[72:73]
	s_add_i32 m0, s28, 0x2000
	s_nop 0
	global_load_lds_dwordx4 v160, s[72:73]
	s_waitcnt vmcnt(6)
	s_barrier
	v_mfma_f32_16x16x32_bf16 v[56:59], v[206:209], v[144:147], v[56:59]
	v_mfma_f32_16x16x32_bf16 v[48:51], v[214:217], v[144:147], v[48:51]
	v_mfma_f32_16x16x32_bf16 v[40:43], v[206:209], v[152:155], v[40:43]
	v_mfma_f32_16x16x32_bf16 v[32:35], v[214:217], v[152:155], v[32:35]
	v_mfma_f32_16x16x32_bf16 v[24:27], v[206:209], v[170:173], v[24:27]
	v_mfma_f32_16x16x32_bf16 v[16:19], v[214:217], v[170:173], v[16:19]
	v_mfma_f32_16x16x32_bf16 v[8:11], v[206:209], v[192:195], v[8:11]
	v_mfma_f32_16x16x32_bf16 v[0:3], v[214:217], v[192:195], v[0:3]
	v_mfma_f32_16x16x32_bf16 v[56:59], v[210:213], v[148:151], v[56:59]
	v_mfma_f32_16x16x32_bf16 v[48:51], v[232:235], v[148:151], v[48:51]
	v_mfma_f32_16x16x32_bf16 v[40:43], v[210:213], v[166:169], v[40:43]
	v_mfma_f32_16x16x32_bf16 v[32:35], v[232:235], v[166:169], v[32:35]
	v_mfma_f32_16x16x32_bf16 v[24:27], v[210:213], v[188:191], v[24:27]
	v_mfma_f32_16x16x32_bf16 v[16:19], v[232:235], v[188:191], v[16:19]
	v_mfma_f32_16x16x32_bf16 v[8:11], v[210:213], v[202:205], v[8:11]
	v_mfma_f32_16x16x32_bf16 v[0:3], v[232:235], v[202:205], v[0:3]
	s_add_i32 s28, 0, 0x18000
	s_barrier
	s_add_u32 s98, s52, 0x40000
	s_addc_u32 s99, s53, 0
	s_mov_b32 m0, s58
	s_nop 0
	global_load_lds_dwordx4 v156, s[98:99]
	s_mov_b32 m0, s59
	s_nop 0
	global_load_lds_dwordx4 v158, s[98:99]
	ds_read_b128 v[128:131], v174 offset:32768
	ds_read_b128 v[132:135], v174 offset:33792
	ds_read_b128 v[136:139], v174 offset:34816
	ds_read_b128 v[140:143], v174 offset:35840
	ds_read_b128 v[144:147], v201 offset:32768
	ds_read_b128 v[152:155], v201 offset:34816
	ds_read_b128 v[170:173], v201 offset:36864
	ds_read_b128 v[192:195], v201 offset:38912
	ds_read_b128 v[148:151], v201 offset:33792
	ds_read_b128 v[166:169], v201 offset:35840
	ds_read_b128 v[188:191], v201 offset:37888
	ds_read_b128 v[202:205], v201 offset:39936
	s_waitcnt lgkmcnt(8)
	s_barrier
	s_waitcnt lgkmcnt(7)
	v_mfma_f32_16x16x32_bf16 v[124:127], v[128:131], v[144:147], v[124:127]
	v_mfma_f32_16x16x32_bf16 v[116:119], v[136:139], v[144:147], v[116:119]
	s_waitcnt lgkmcnt(6)
	v_mfma_f32_16x16x32_bf16 v[108:111], v[128:131], v[152:155], v[108:111]
	v_mfma_f32_16x16x32_bf16 v[100:103], v[136:139], v[152:155], v[100:103]
	s_waitcnt lgkmcnt(5)
	v_mfma_f32_16x16x32_bf16 v[92:95], v[128:131], v[170:173], v[92:95]
	v_mfma_f32_16x16x32_bf16 v[84:87], v[136:139], v[170:173], v[84:87]
	s_waitcnt lgkmcnt(4)
	v_mfma_f32_16x16x32_bf16 v[76:79], v[128:131], v[192:195], v[76:79]
	v_mfma_f32_16x16x32_bf16 v[68:71], v[136:139], v[192:195], v[68:71]
	s_waitcnt lgkmcnt(3)
	v_mfma_f32_16x16x32_bf16 v[124:127], v[132:135], v[148:151], v[124:127]
	v_mfma_f32_16x16x32_bf16 v[116:119], v[140:143], v[148:151], v[116:119]
	s_waitcnt lgkmcnt(2)
	v_mfma_f32_16x16x32_bf16 v[108:111], v[132:135], v[166:169], v[108:111]
	v_mfma_f32_16x16x32_bf16 v[100:103], v[140:143], v[166:169], v[100:103]
	s_waitcnt lgkmcnt(1)
	v_mfma_f32_16x16x32_bf16 v[92:95], v[132:135], v[188:191], v[92:95]
	v_mfma_f32_16x16x32_bf16 v[84:87], v[140:143], v[188:191], v[84:87]
	s_waitcnt lgkmcnt(0)
	v_mfma_f32_16x16x32_bf16 v[76:79], v[132:135], v[202:205], v[76:79]
	v_mfma_f32_16x16x32_bf16 v[68:71], v[140:143], v[202:205], v[68:71]
	s_barrier
	s_add_i32 s29, 0, 0x1c000
	s_add_i32 s28, s28, s55
	s_add_i32 m0, s28, 0xffffff80
	s_nop 0
	global_load_lds_dwordx4 v176, s[50:51] offset:128
	s_add_i32 m0, s28, 0x1f80
	s_nop 0
	global_load_lds_dwordx4 v160, s[50:51] offset:128
	ds_read_b128 v[206:209], v174 offset:49152
	ds_read_b128 v[210:213], v174 offset:50176
	ds_read_b128 v[214:217], v174 offset:51200
	ds_read_b128 v[232:235], v174 offset:52224
	s_barrier
	s_waitcnt lgkmcnt(3)
	v_mfma_f32_16x16x32_bf16 v[120:123], v[206:209], v[144:147], v[120:123]
	s_waitcnt lgkmcnt(1)
	v_mfma_f32_16x16x32_bf16 v[112:115], v[214:217], v[144:147], v[112:115]
	v_mfma_f32_16x16x32_bf16 v[104:107], v[206:209], v[152:155], v[104:107]
	v_mfma_f32_16x16x32_bf16 v[96:99], v[214:217], v[152:155], v[96:99]
	v_mfma_f32_16x16x32_bf16 v[88:91], v[206:209], v[170:173], v[88:91]
	v_mfma_f32_16x16x32_bf16 v[80:83], v[214:217], v[170:173], v[80:83]
	v_mfma_f32_16x16x32_bf16 v[72:75], v[206:209], v[192:195], v[72:75]
	v_mfma_f32_16x16x32_bf16 v[64:67], v[214:217], v[192:195], v[64:67]
	v_mfma_f32_16x16x32_bf16 v[120:123], v[210:213], v[148:151], v[120:123]
	s_waitcnt lgkmcnt(0)
	v_mfma_f32_16x16x32_bf16 v[112:115], v[232:235], v[148:151], v[112:115]
	v_mfma_f32_16x16x32_bf16 v[104:107], v[210:213], v[166:169], v[104:107]
	v_mfma_f32_16x16x32_bf16 v[96:99], v[232:235], v[166:169], v[96:99]
	v_mfma_f32_16x16x32_bf16 v[88:91], v[210:213], v[188:191], v[88:91]
	v_mfma_f32_16x16x32_bf16 v[80:83], v[232:235], v[188:191], v[80:83]
	v_mfma_f32_16x16x32_bf16 v[72:75], v[210:213], v[202:205], v[72:75]
	v_mfma_f32_16x16x32_bf16 v[64:67], v[232:235], v[202:205], v[64:67]
	s_add_i32 m0, s62, 0xffffff80
	s_barrier
	global_load_lds_dwordx4 v156, s[52:53] offset:128
	s_add_i32 m0, s63, 0xffffff80
	s_nop 0
	global_load_lds_dwordx4 v158, s[52:53] offset:128
	ds_read_b128 v[144:147], v201 offset:49152
	ds_read_b128 v[152:155], v201 offset:51200
	ds_read_b128 v[170:173], v201 offset:53248
	ds_read_b128 v[192:195], v201 offset:55296
	ds_read_b128 v[148:151], v201 offset:50176
	ds_read_b128 v[166:169], v201 offset:52224
	ds_read_b128 v[188:191], v201 offset:54272
	ds_read_b128 v[202:205], v201 offset:56320
	s_barrier
	s_waitcnt lgkmcnt(7)
	v_mfma_f32_16x16x32_bf16 v[60:63], v[128:131], v[144:147], v[60:63]
	v_mfma_f32_16x16x32_bf16 v[52:55], v[136:139], v[144:147], v[52:55]
	s_waitcnt lgkmcnt(6)
	v_mfma_f32_16x16x32_bf16 v[44:47], v[128:131], v[152:155], v[44:47]
	v_mfma_f32_16x16x32_bf16 v[36:39], v[136:139], v[152:155], v[36:39]
	s_waitcnt lgkmcnt(5)
	v_mfma_f32_16x16x32_bf16 v[28:31], v[128:131], v[170:173], v[28:31]
	v_mfma_f32_16x16x32_bf16 v[20:23], v[136:139], v[170:173], v[20:23]
	s_waitcnt lgkmcnt(4)
	v_mfma_f32_16x16x32_bf16 v[12:15], v[128:131], v[192:195], v[12:15]
	v_mfma_f32_16x16x32_bf16 v[4:7], v[136:139], v[192:195], v[4:7]
	s_waitcnt lgkmcnt(3)
	v_mfma_f32_16x16x32_bf16 v[60:63], v[132:135], v[148:151], v[60:63]
	v_mfma_f32_16x16x32_bf16 v[52:55], v[140:143], v[148:151], v[52:55]
	s_waitcnt lgkmcnt(2)
	v_mfma_f32_16x16x32_bf16 v[44:47], v[132:135], v[166:169], v[44:47]
	v_mfma_f32_16x16x32_bf16 v[36:39], v[140:143], v[166:169], v[36:39]
	s_waitcnt lgkmcnt(1)
	v_mfma_f32_16x16x32_bf16 v[28:31], v[132:135], v[188:191], v[28:31]
	v_mfma_f32_16x16x32_bf16 v[20:23], v[140:143], v[188:191], v[20:23]
	s_waitcnt lgkmcnt(0)
	v_mfma_f32_16x16x32_bf16 v[12:15], v[132:135], v[202:205], v[12:15]
	v_mfma_f32_16x16x32_bf16 v[4:7], v[140:143], v[202:205], v[4:7]
	s_barrier
	s_add_u32 s50, s50, 0x40080
	s_addc_u32 s51, s51, 0
	s_add_i32 s28, s29, s55
	s_mov_b32 m0, s28
	s_nop 0
	global_load_lds_dwordx4 v176, s[50:51]
	s_add_i32 m0, s28, 0x2000
	s_nop 0
	global_load_lds_dwordx4 v160, s[50:51]
	s_waitcnt vmcnt(6)
	s_barrier
	v_mfma_f32_16x16x32_bf16 v[56:59], v[206:209], v[144:147], v[56:59]
	v_mfma_f32_16x16x32_bf16 v[48:51], v[214:217], v[144:147], v[48:51]
	v_mfma_f32_16x16x32_bf16 v[40:43], v[206:209], v[152:155], v[40:43]
	v_mfma_f32_16x16x32_bf16 v[32:35], v[214:217], v[152:155], v[32:35]
	v_mfma_f32_16x16x32_bf16 v[24:27], v[206:209], v[170:173], v[24:27]
	v_mfma_f32_16x16x32_bf16 v[16:19], v[214:217], v[170:173], v[16:19]
	v_mfma_f32_16x16x32_bf16 v[8:11], v[206:209], v[192:195], v[8:11]
	v_mfma_f32_16x16x32_bf16 v[0:3], v[214:217], v[192:195], v[0:3]
	v_mfma_f32_16x16x32_bf16 v[56:59], v[210:213], v[148:151], v[56:59]
	v_mfma_f32_16x16x32_bf16 v[48:51], v[232:235], v[148:151], v[48:51]
	v_mfma_f32_16x16x32_bf16 v[40:43], v[210:213], v[166:169], v[40:43]
	v_mfma_f32_16x16x32_bf16 v[32:35], v[232:235], v[166:169], v[32:35]
	v_mfma_f32_16x16x32_bf16 v[24:27], v[210:213], v[188:191], v[24:27]
	v_mfma_f32_16x16x32_bf16 v[16:19], v[232:235], v[188:191], v[16:19]
	v_mfma_f32_16x16x32_bf16 v[8:11], v[210:213], v[202:205], v[8:11]
	v_mfma_f32_16x16x32_bf16 v[0:3], v[232:235], v[202:205], v[0:3]
	s_add_i32 s70, s70, 2
	s_add_u32 s6, s6, 0x100
	s_addc_u32 s7, s7, 0
	s_add_u32 s68, s68, 0x100
	s_addc_u32 s69, s69, 0
	s_cmp_lt_u32 s70, 14
	s_barrier
	s_cbranch_scc1 .LBB0_1436
	v_mov_b32_e32 v134, v199
	v_mov_b32_e32 v128, v198
	s_lshl_b32 s4, s4, 8
	s_add_i32 s4, s4, s60
	v_add_u32_e32 v192, s4, v128
	v_lshlrev_b32_e32 v128, 2, v134
	v_ashrrev_i32_e32 v129, 31, v128
	v_ashrrev_i32_e32 v193, 31, v192
	v_add_u32_e32 v190, 16, v192
	v_lshl_add_u64 v[132:133], v[128:129], 2, s[8:9]
	v_lshlrev_b64 v[128:129], 6, v[192:193]
	v_ashrrev_i32_e32 v191, 31, v190
	v_add_u32_e32 v188, 32, v192
	v_lshl_add_u64 v[128:129], v[132:133], 0, v[128:129]
	v_lshlrev_b64 v[130:131], 6, v[190:191]
	v_ashrrev_i32_e32 v189, 31, v188
	v_lshl_add_u64 v[130:131], v[132:133], 0, v[130:131]
	global_load_dwordx4 v[202:205], v[128:129], off
	global_load_dwordx4 v[144:147], v[130:131], off
	v_lshlrev_b64 v[128:129], 6, v[188:189]
	v_add_u32_e32 v174, 48, v192
	v_lshl_add_u64 v[128:129], v[132:133], 0, v[128:129]
	v_ashrrev_i32_e32 v175, 31, v174
	global_load_dwordx4 v[148:151], v[128:129], off
	v_lshlrev_b64 v[128:129], 6, v[174:175]
	v_lshl_add_u64 v[128:129], v[132:133], 0, v[128:129]
	global_load_dwordx4 v[152:155], v[128:129], off
	v_add_u32_e32 v172, 0x80, v192
	v_ashrrev_i32_e32 v173, 31, v172
	v_lshlrev_b64 v[128:129], 6, v[172:173]
	v_lshl_add_u64 v[128:129], v[132:133], 0, v[128:129]
	global_load_dwordx4 v[140:143], v[128:129], off
	v_add_u32_e32 v170, 0x90, v192
	v_ashrrev_i32_e32 v171, 31, v170
	v_lshlrev_b64 v[128:129], 6, v[170:171]
	v_lshl_add_u64 v[128:129], v[132:133], 0, v[128:129]
	global_load_dwordx4 v[128:131], v[128:129], off
	s_lshl_b32 s5, s5, 7
	v_add_u32_e32 v168, 0xa0, v192
	v_add_u32_e32 v166, 0xb0, v192
	s_or_b32 s5, s5, s61
	v_ashrrev_i32_e32 v169, 31, v168
	v_ashrrev_i32_e32 v167, 31, v166
	v_lshl_add_u32 v194, v134, 3, s5
	v_lshlrev_b64 v[134:135], 6, v[168:169]
	v_lshlrev_b64 v[136:137], 6, v[166:167]
	v_lshl_add_u64 v[134:135], v[132:133], 0, v[134:135]
	v_lshl_add_u64 v[132:133], v[132:133], 0, v[136:137]
	global_load_dwordx4 v[136:139], v[134:135], off
	s_nop 0
	global_load_dwordx4 v[132:135], v[132:133], off
	s_mov_b32 s4, 0x358637bd
	v_mov_b64_e32 v[196:197], s[4:5]
	v_ashrrev_i32_e32 v195, 31, v194
	s_mov_b64 s[50:51], s[20:21]
	s_waitcnt vmcnt(0)
	v_mov_b32_e32 v206, v203
	v_mov_b32_e32 v207, v204
	v_mov_b32_e32 v203, v205
	v_mov_b32_e32 v204, v145
	v_mov_b32_e32 v205, v146
	v_mov_b32_e32 v145, v147
	v_pk_add_f32 v[202:203], v[206:207], v[202:203]
	v_mov_b32_e32 v146, v149
	v_mov_b32_e32 v147, v150
	v_mov_b32_e32 v149, v151
	v_mov_b32_e32 v150, v153
	v_mov_b32_e32 v151, v154
	v_mov_b32_e32 v153, v155
	v_pk_add_f32 v[144:145], v[204:205], v[144:145]
	v_mov_b32_e32 v155, v202
	v_pk_add_f32 v[146:147], v[146:147], v[148:149]
	v_pk_add_f32 v[148:149], v[150:151], v[152:153]
	v_mov_b32_e32 v154, v144
	v_mov_b32_e32 v202, v145
	v_mov_b32_e32 v144, v148
	v_mov_b32_e32 v145, v146
	v_mov_b32_e32 v146, v149
	v_pk_add_f32 v[148:149], v[154:155], v[202:203]
	v_pk_add_f32 v[144:145], v[144:145], v[146:147]
	ds_bpermute_b32 v147, v219, v149
	ds_bpermute_b32 v146, v219, v148
	ds_bpermute_b32 v151, v219, v145
	ds_bpermute_b32 v150, v219, v144
	v_mov_b32_e32 v152, v141
	v_mov_b32_e32 v153, v142
	v_mov_b32_e32 v141, v143
	s_waitcnt lgkmcnt(0)
	v_pk_add_f32 v[142:143], v[148:149], v[146:147]
	ds_bpermute_b32 v147, v218, v143
	ds_bpermute_b32 v146, v218, v142
	v_pk_add_f32 v[144:145], v[144:145], v[150:151]
	ds_bpermute_b32 v149, v218, v145
	ds_bpermute_b32 v148, v218, v144
	v_mov_b32_e32 v150, v129
	s_waitcnt lgkmcnt(2)
	v_pk_add_f32 v[142:143], v[142:143], v[146:147]
	v_mov_b32_e32 v151, v130
	v_pk_fma_f32 v[142:143], v[142:143], s[30:31], v[196:197] op_sel_hi:[1,0,0]
	s_waitcnt lgkmcnt(0)
	v_pk_add_f32 v[144:145], v[144:145], v[148:149]
	v_mul_f32_e32 v129, 0x4b800000, v143
	v_cmp_gt_f32_e32 vcc, s86, v143
	v_pk_fma_f32 v[146:147], v[144:145], s[30:31], v[196:197] op_sel_hi:[1,0,0]
	v_mul_f32_e32 v130, 0x4b800000, v142
	v_cndmask_b32_e32 v129, v143, v129, vcc
	v_rsq_f32_e32 v129, v129
	v_cmp_gt_f32_e64 s[4:5], s86, v142
	v_mul_f32_e32 v144, 0x4b800000, v147
	v_cmp_gt_f32_e64 s[6:7], s86, v147
	v_cndmask_b32_e64 v130, v142, v130, s[4:5]
	v_rsq_f32_e32 v142, v130
	v_cndmask_b32_e64 v130, v147, v144, s[6:7]
	v_rsq_f32_e32 v143, v130
	v_mul_f32_e32 v130, 0x45800000, v129
	v_cndmask_b32_e32 v144, v129, v130, vcc
	v_mov_b32_e32 v129, v131
	v_pk_add_f32 v[140:141], v[152:153], v[140:141]
	v_pk_add_f32 v[128:129], v[150:151], v[128:129]
	v_mov_b32_e32 v131, v140
	v_mov_b32_e32 v130, v128
	v_mov_b32_e32 v140, v129
	v_pk_add_f32 v[128:129], v[130:131], v[140:141]
	ds_bpermute_b32 v131, v219, v129
	ds_bpermute_b32 v130, v219, v128
	v_mul_f32_e32 v145, 0x45800000, v142
	v_cndmask_b32_e64 v142, v142, v145, s[4:5]
	v_mul_f32_e32 v140, 0x4b800000, v146
	v_cmp_gt_f32_e32 vcc, s86, v146
	s_waitcnt lgkmcnt(0)
	v_pk_add_f32 v[128:129], v[128:129], v[130:131]
	ds_bpermute_b32 v131, v218, v129
	ds_bpermute_b32 v130, v218, v128
	v_cndmask_b32_e32 v140, v146, v140, vcc
	v_rsq_f32_e32 v141, v140
	v_mul_f32_e32 v140, 0x45800000, v143
	v_cndmask_b32_e64 v140, v143, v140, s[6:7]
	s_waitcnt lgkmcnt(0)
	v_pk_add_f32 v[128:129], v[128:129], v[130:131]
	v_mov_b32_e32 v131, v138
	v_pk_fma_f32 v[128:129], v[128:129], s[30:31], v[196:197] op_sel_hi:[1,0,0]
	v_mul_f32_e32 v143, 0x45800000, v141
	v_mul_f32_e32 v130, 0x4b800000, v129
	v_cmp_gt_f32_e64 s[4:5], s86, v129
	v_cmp_gt_f32_e64 s[6:7], s86, v128
	v_pk_mul_f32 v[110:111], v[110:111], v[142:143] op_sel_hi:[1,0]
	v_cndmask_b32_e64 v129, v129, v130, s[4:5]
	v_mov_b32_e32 v130, v137
	v_mov_b32_e32 v137, v139
	v_pk_add_f32 v[130:131], v[130:131], v[136:137]
	v_mov_b32_e32 v136, v133
	v_mov_b32_e32 v137, v134
	v_mov_b32_e32 v133, v135
	v_pk_add_f32 v[132:133], v[136:137], v[132:133]
	v_mov_b32_e32 v135, v130
	v_mov_b32_e32 v134, v132
	v_mov_b32_e32 v130, v133
	v_pk_add_f32 v[130:131], v[134:135], v[130:131]
	ds_bpermute_b32 v133, v219, v131
	ds_bpermute_b32 v132, v219, v130
	v_rsq_f32_e32 v145, v129
	v_mul_f32_e32 v129, 0x4b800000, v128
	v_cndmask_b32_e64 v128, v128, v129, s[6:7]
	v_rsq_f32_e32 v135, v128
	s_waitcnt lgkmcnt(0)
	v_pk_add_f32 v[128:129], v[130:131], v[132:133]
	ds_bpermute_b32 v131, v218, v129
	ds_bpermute_b32 v130, v218, v128
	v_pk_mul_f32 v[126:127], v[126:127], v[144:145] op_sel_hi:[1,0]
	v_pk_mul_f32 v[122:123], v[122:123], v[144:145] op_sel_hi:[1,0]
	v_pk_mul_f32 v[116:117], v[116:117], v[144:145] op_sel_hi:[1,0]
	v_pk_mul_f32 v[124:125], v[124:125], v[144:145] op_sel_hi:[1,0]
	v_pk_mul_f32 v[138:139], v[126:127], s[44:45] op_sel_hi:[1,0]
	v_pk_mul_f32 v[120:121], v[120:121], v[144:145] op_sel_hi:[1,0]
	v_pk_mul_f32 v[122:123], v[126:127], v[122:123]
	v_pk_mul_f32 v[118:119], v[118:119], v[144:145] op_sel_hi:[1,0]
	v_pk_mul_f32 v[126:127], v[116:117], s[44:45] op_sel_hi:[1,0]
	v_pk_mul_f32 v[146:147], v[124:125], s[44:45] op_sel_hi:[1,0]
	v_pk_mul_f32 v[120:121], v[124:125], v[120:121]
	v_pk_mul_f32 v[124:125], v[118:119], s[44:45] op_sel_hi:[1,0]
	v_exp_f32_e32 v126, v126
	v_exp_f32_e32 v127, v127
	s_waitcnt lgkmcnt(0)
	v_pk_add_f32 v[128:129], v[128:129], v[130:131]
	v_exp_f32_e32 v146, v146
	v_exp_f32_e32 v138, v138
	v_exp_f32_e32 v139, v139
	v_exp_f32_e32 v147, v147
	v_exp_f32_e32 v124, v124
	v_exp_f32_e32 v125, v125
	v_pk_fma_f32 v[128:129], v[128:129], s[30:31], v[196:197] op_sel_hi:[1,0,0]
	v_cndmask_b32_e32 v136, v141, v143, vcc
	v_mul_f32_e32 v132, 0x45800000, v145
	v_mul_f32_e32 v130, 0x4b800000, v129
	v_cmp_gt_f32_e32 vcc, s86, v129
	v_cndmask_b32_e64 v134, v145, v132, s[4:5]
	v_cmp_gt_f32_e64 s[4:5], s86, v128
	v_cndmask_b32_e32 v129, v129, v130, vcc
	v_mul_f32_e32 v130, 0x4b800000, v128
	v_pk_add_f32 v[126:127], v[126:127], 1.0 op_sel_hi:[1,0]
	v_rsq_f32_e32 v129, v129
	v_cndmask_b32_e64 v128, v128, v130, s[4:5]
	v_pk_add_f32 v[138:139], v[138:139], 1.0 op_sel_hi:[1,0]
	v_pk_add_f32 v[146:147], v[146:147], 1.0 op_sel_hi:[1,0]
	v_pk_add_f32 v[124:125], v[124:125], 1.0 op_sel_hi:[1,0]
	v_rcp_f32_e32 v126, v126
	v_rcp_f32_e32 v127, v127
	v_rsq_f32_e32 v128, v128
	v_rcp_f32_e32 v146, v146
	v_rcp_f32_e32 v138, v138
	v_rcp_f32_e32 v139, v139
	v_rcp_f32_e32 v147, v147
	v_rcp_f32_e32 v124, v124
	v_rcp_f32_e32 v125, v125
	v_pk_mul_f32 v[112:113], v[112:113], v[144:145] op_sel_hi:[1,0]
	v_pk_mul_f32 v[114:115], v[114:115], v[144:145] op_sel_hi:[1,0]
	v_pk_mul_f32 v[112:113], v[116:117], v[112:113]
	v_mul_f32_e32 v130, 0x45800000, v129
	v_pk_mul_f32 v[114:115], v[118:119], v[114:115]
	v_pk_mul_f32 v[112:113], v[112:113], v[126:127]
	v_cndmask_b32_e32 v130, v129, v130, vcc
	v_mul_f32_e32 v129, 0x45800000, v128
	v_pk_mul_f32 v[122:123], v[122:123], v[138:139]
	v_pk_mul_f32 v[120:121], v[120:121], v[146:147]
	v_pk_mul_f32 v[114:115], v[114:115], v[124:125]
	v_cvt_pk_bf16_f32 v116, v120, v121
	v_cvt_pk_bf16_f32 v117, v122, v123
	v_cvt_pk_bf16_f32 v118, v112, v113
	v_mov_b64_e32 v[112:113], s[10:11]
	v_cndmask_b32_e64 v128, v128, v129, s[4:5]
	v_cvt_pk_bf16_f32 v119, v114, v115
	v_mad_i64_i32 v[120:121], s[4:5], v192, s35, v[112:113]
	v_lshlrev_b64 v[114:115], 1, v[194:195]
	v_lshl_add_u64 v[120:121], v[120:121], 0, v[114:115]
	v_pk_mul_f32 v[108:109], v[108:109], v[142:143] op_sel_hi:[1,0]
	v_pk_mul_f32 v[106:107], v[106:107], v[142:143] op_sel_hi:[1,0]
	v_pk_mul_f32 v[104:105], v[104:105], v[142:143] op_sel_hi:[1,0]
	v_pk_mul_f32 v[102:103], v[102:103], v[142:143] op_sel_hi:[1,0]
	v_pk_mul_f32 v[100:101], v[100:101], v[142:143] op_sel_hi:[1,0]
	global_store_dwordx4 v[120:121], v[116:119], off
	v_pk_mul_f32 v[104:105], v[108:109], v[104:105]
	v_pk_mul_f32 v[106:107], v[110:111], v[106:107]
	v_pk_mul_f32 v[116:117], v[110:111], s[44:45] op_sel_hi:[1,0]
	v_pk_mul_f32 v[118:119], v[108:109], s[44:45] op_sel_hi:[1,0]
	v_pk_mul_f32 v[108:109], v[102:103], s[44:45] op_sel_hi:[1,0]
	v_pk_mul_f32 v[110:111], v[100:101], s[44:45] op_sel_hi:[1,0]
	v_exp_f32_e32 v108, v108
	v_exp_f32_e32 v110, v110
	v_exp_f32_e32 v109, v109
	v_exp_f32_e32 v111, v111
	v_exp_f32_e32 v118, v118
	v_exp_f32_e32 v116, v116
	v_exp_f32_e32 v117, v117
	v_exp_f32_e32 v119, v119
	v_pk_add_f32 v[108:109], v[108:109], 1.0 op_sel_hi:[1,0]
	v_pk_add_f32 v[110:111], v[110:111], 1.0 op_sel_hi:[1,0]
	v_pk_add_f32 v[116:117], v[116:117], 1.0 op_sel_hi:[1,0]
	v_pk_add_f32 v[118:119], v[118:119], 1.0 op_sel_hi:[1,0]
	v_rcp_f32_e32 v110, v110
	v_rcp_f32_e32 v108, v108
	v_rcp_f32_e32 v109, v109
	v_rcp_f32_e32 v111, v111
	v_rcp_f32_e32 v118, v118
	v_rcp_f32_e32 v116, v116
	v_rcp_f32_e32 v117, v117
	v_rcp_f32_e32 v119, v119
	v_pk_mul_f32 v[98:99], v[98:99], v[142:143] op_sel_hi:[1,0]
	v_pk_mul_f32 v[96:97], v[96:97], v[142:143] op_sel_hi:[1,0]
	v_pk_mul_f32 v[98:99], v[102:103], v[98:99]
	v_pk_mul_f32 v[96:97], v[100:101], v[96:97]
	v_pk_mul_f32 v[100:101], v[98:99], v[108:109]
	v_pk_mul_f32 v[98:99], v[96:97], v[110:111]
	v_pk_mul_f32 v[106:107], v[106:107], v[116:117]
	v_pk_mul_f32 v[104:105], v[104:105], v[118:119]
	v_pk_mul_f32 v[94:95], v[94:95], v[140:141] op_sel_hi:[1,0]
	v_cvt_pk_bf16_f32 v96, v104, v105
	v_cvt_pk_bf16_f32 v97, v106, v107
	v_cvt_pk_bf16_f32 v98, v98, v99
	v_cvt_pk_bf16_f32 v99, v100, v101
	v_mad_i64_i32 v[100:101], s[4:5], v190, s35, v[112:113]
	v_lshl_add_u64 v[100:101], v[100:101], 0, v[114:115]
	v_pk_mul_f32 v[92:93], v[92:93], v[140:141] op_sel_hi:[1,0]
	v_pk_mul_f32 v[90:91], v[90:91], v[140:141] op_sel_hi:[1,0]
	v_pk_mul_f32 v[88:89], v[88:89], v[140:141] op_sel_hi:[1,0]
	v_pk_mul_f32 v[86:87], v[86:87], v[140:141] op_sel_hi:[1,0]
	v_pk_mul_f32 v[84:85], v[84:85], v[140:141] op_sel_hi:[1,0]
	global_store_dwordx4 v[100:101], v[96:99], off
	v_pk_mul_f32 v[88:89], v[92:93], v[88:89]
	v_pk_mul_f32 v[90:91], v[94:95], v[90:91]
	v_pk_mul_f32 v[96:97], v[94:95], s[44:45] op_sel_hi:[1,0]
	v_pk_mul_f32 v[98:99], v[92:93], s[44:45] op_sel_hi:[1,0]
	v_pk_mul_f32 v[92:93], v[86:87], s[44:45] op_sel_hi:[1,0]
	v_pk_mul_f32 v[94:95], v[84:85], s[44:45] op_sel_hi:[1,0]
	v_exp_f32_e32 v92, v92
	v_exp_f32_e32 v94, v94
	v_exp_f32_e32 v93, v93
	v_exp_f32_e32 v95, v95
	v_exp_f32_e32 v98, v98
	v_exp_f32_e32 v96, v96
	v_exp_f32_e32 v97, v97
	v_exp_f32_e32 v99, v99
	v_pk_add_f32 v[92:93], v[92:93], 1.0 op_sel_hi:[1,0]
	v_pk_add_f32 v[94:95], v[94:95], 1.0 op_sel_hi:[1,0]
	v_pk_add_f32 v[96:97], v[96:97], 1.0 op_sel_hi:[1,0]
	v_pk_add_f32 v[98:99], v[98:99], 1.0 op_sel_hi:[1,0]
	v_rcp_f32_e32 v94, v94
	v_rcp_f32_e32 v92, v92
	v_rcp_f32_e32 v93, v93
	v_rcp_f32_e32 v95, v95
	v_rcp_f32_e32 v98, v98
	v_rcp_f32_e32 v96, v96
	v_rcp_f32_e32 v97, v97
	v_rcp_f32_e32 v99, v99
	v_pk_mul_f32 v[82:83], v[82:83], v[140:141] op_sel_hi:[1,0]
	v_pk_mul_f32 v[80:81], v[80:81], v[140:141] op_sel_hi:[1,0]
	v_pk_mul_f32 v[82:83], v[86:87], v[82:83]
	v_pk_mul_f32 v[80:81], v[84:85], v[80:81]
	v_pk_mul_f32 v[84:85], v[82:83], v[92:93]
	v_pk_mul_f32 v[82:83], v[80:81], v[94:95]
	v_pk_mul_f32 v[90:91], v[90:91], v[96:97]
	v_pk_mul_f32 v[88:89], v[88:89], v[98:99]
	v_pk_mul_f32 v[78:79], v[78:79], v[136:137] op_sel_hi:[1,0]
	v_cvt_pk_bf16_f32 v80, v88, v89
	v_cvt_pk_bf16_f32 v81, v90, v91
	v_cvt_pk_bf16_f32 v82, v82, v83
	v_cvt_pk_bf16_f32 v83, v84, v85
	v_mad_i64_i32 v[84:85], s[4:5], v188, s35, v[112:113]
	v_lshl_add_u64 v[84:85], v[84:85], 0, v[114:115]
	v_pk_mul_f32 v[76:77], v[76:77], v[136:137] op_sel_hi:[1,0]
	v_pk_mul_f32 v[74:75], v[74:75], v[136:137] op_sel_hi:[1,0]
	v_pk_mul_f32 v[72:73], v[72:73], v[136:137] op_sel_hi:[1,0]
	v_pk_mul_f32 v[70:71], v[70:71], v[136:137] op_sel_hi:[1,0]
	v_pk_mul_f32 v[68:69], v[68:69], v[136:137] op_sel_hi:[1,0]
	global_store_dwordx4 v[84:85], v[80:83], off
	v_pk_mul_f32 v[72:73], v[76:77], v[72:73]
	v_pk_mul_f32 v[74:75], v[78:79], v[74:75]
	v_pk_mul_f32 v[80:81], v[78:79], s[44:45] op_sel_hi:[1,0]
	v_pk_mul_f32 v[82:83], v[76:77], s[44:45] op_sel_hi:[1,0]
	v_pk_mul_f32 v[76:77], v[70:71], s[44:45] op_sel_hi:[1,0]
	v_pk_mul_f32 v[78:79], v[68:69], s[44:45] op_sel_hi:[1,0]
	v_exp_f32_e32 v76, v76
	v_exp_f32_e32 v78, v78
	v_exp_f32_e32 v77, v77
	v_exp_f32_e32 v79, v79
	v_exp_f32_e32 v82, v82
	v_exp_f32_e32 v80, v80
	v_exp_f32_e32 v81, v81
	v_exp_f32_e32 v83, v83
	v_pk_add_f32 v[76:77], v[76:77], 1.0 op_sel_hi:[1,0]
	v_pk_add_f32 v[78:79], v[78:79], 1.0 op_sel_hi:[1,0]
	v_pk_add_f32 v[80:81], v[80:81], 1.0 op_sel_hi:[1,0]
	v_pk_add_f32 v[82:83], v[82:83], 1.0 op_sel_hi:[1,0]
	v_rcp_f32_e32 v78, v78
	v_rcp_f32_e32 v76, v76
	v_rcp_f32_e32 v77, v77
	v_rcp_f32_e32 v79, v79
	v_rcp_f32_e32 v82, v82
	v_rcp_f32_e32 v80, v80
	v_rcp_f32_e32 v81, v81
	v_rcp_f32_e32 v83, v83
	v_pk_mul_f32 v[66:67], v[66:67], v[136:137] op_sel_hi:[1,0]
	v_pk_mul_f32 v[64:65], v[64:65], v[136:137] op_sel_hi:[1,0]
	v_pk_mul_f32 v[66:67], v[70:71], v[66:67]
	v_pk_mul_f32 v[64:65], v[68:69], v[64:65]
	v_pk_mul_f32 v[68:69], v[66:67], v[76:77]
	v_pk_mul_f32 v[66:67], v[64:65], v[78:79]
	v_pk_mul_f32 v[74:75], v[74:75], v[80:81]
	v_pk_mul_f32 v[72:73], v[72:73], v[82:83]
	v_pk_mul_f32 v[62:63], v[62:63], v[134:135] op_sel_hi:[1,0]
	v_cvt_pk_bf16_f32 v64, v72, v73
	v_cvt_pk_bf16_f32 v65, v74, v75
	v_cvt_pk_bf16_f32 v66, v66, v67
	v_cvt_pk_bf16_f32 v67, v68, v69
	v_mad_i64_i32 v[68:69], s[4:5], v174, s35, v[112:113]
	v_lshl_add_u64 v[68:69], v[68:69], 0, v[114:115]
	v_pk_mul_f32 v[60:61], v[60:61], v[134:135] op_sel_hi:[1,0]
	v_pk_mul_f32 v[58:59], v[58:59], v[134:135] op_sel_hi:[1,0]
	v_pk_mul_f32 v[56:57], v[56:57], v[134:135] op_sel_hi:[1,0]
	v_pk_mul_f32 v[54:55], v[54:55], v[134:135] op_sel_hi:[1,0]
	v_pk_mul_f32 v[52:53], v[52:53], v[134:135] op_sel_hi:[1,0]
	global_store_dwordx4 v[68:69], v[64:67], off
	v_pk_mul_f32 v[56:57], v[60:61], v[56:57]
	v_pk_mul_f32 v[58:59], v[62:63], v[58:59]
	v_pk_mul_f32 v[64:65], v[62:63], s[44:45] op_sel_hi:[1,0]
	v_pk_mul_f32 v[66:67], v[60:61], s[44:45] op_sel_hi:[1,0]
	v_pk_mul_f32 v[60:61], v[54:55], s[44:45] op_sel_hi:[1,0]
	v_pk_mul_f32 v[62:63], v[52:53], s[44:45] op_sel_hi:[1,0]
	v_exp_f32_e32 v60, v60
	v_exp_f32_e32 v62, v62
	v_exp_f32_e32 v61, v61
	v_exp_f32_e32 v63, v63
	v_exp_f32_e32 v66, v66
	v_exp_f32_e32 v64, v64
	v_exp_f32_e32 v65, v65
	v_exp_f32_e32 v67, v67
	v_pk_add_f32 v[60:61], v[60:61], 1.0 op_sel_hi:[1,0]
	v_pk_add_f32 v[62:63], v[62:63], 1.0 op_sel_hi:[1,0]
	v_pk_add_f32 v[64:65], v[64:65], 1.0 op_sel_hi:[1,0]
	v_pk_add_f32 v[66:67], v[66:67], 1.0 op_sel_hi:[1,0]
	v_rcp_f32_e32 v62, v62
	v_rcp_f32_e32 v60, v60
	v_rcp_f32_e32 v61, v61
	v_rcp_f32_e32 v63, v63
	v_rcp_f32_e32 v66, v66
	v_rcp_f32_e32 v64, v64
	v_rcp_f32_e32 v65, v65
	v_rcp_f32_e32 v67, v67
	v_pk_mul_f32 v[50:51], v[50:51], v[134:135] op_sel_hi:[1,0]
	v_pk_mul_f32 v[48:49], v[48:49], v[134:135] op_sel_hi:[1,0]
	v_pk_mul_f32 v[50:51], v[54:55], v[50:51]
	v_pk_mul_f32 v[48:49], v[52:53], v[48:49]
	v_mul_f32_e32 v132, 0x45800000, v135
	v_pk_mul_f32 v[52:53], v[50:51], v[60:61]
	v_pk_mul_f32 v[50:51], v[48:49], v[62:63]
	v_cndmask_b32_e64 v132, v135, v132, s[6:7]
	v_pk_mul_f32 v[58:59], v[58:59], v[64:65]
	v_pk_mul_f32 v[56:57], v[56:57], v[66:67]
	v_pk_mul_f32 v[46:47], v[46:47], v[132:133] op_sel_hi:[1,0]
	v_cvt_pk_bf16_f32 v48, v56, v57
	v_cvt_pk_bf16_f32 v49, v58, v59
	v_cvt_pk_bf16_f32 v50, v50, v51
	v_cvt_pk_bf16_f32 v51, v52, v53
	v_mad_i64_i32 v[52:53], s[4:5], v172, s35, v[112:113]
	v_lshl_add_u64 v[52:53], v[52:53], 0, v[114:115]
	v_pk_mul_f32 v[44:45], v[44:45], v[132:133] op_sel_hi:[1,0]
	v_pk_mul_f32 v[42:43], v[42:43], v[132:133] op_sel_hi:[1,0]
	v_pk_mul_f32 v[40:41], v[40:41], v[132:133] op_sel_hi:[1,0]
	v_pk_mul_f32 v[38:39], v[38:39], v[132:133] op_sel_hi:[1,0]
	v_pk_mul_f32 v[36:37], v[36:37], v[132:133] op_sel_hi:[1,0]
	global_store_dwordx4 v[52:53], v[48:51], off
	v_pk_mul_f32 v[40:41], v[44:45], v[40:41]
	v_pk_mul_f32 v[42:43], v[46:47], v[42:43]
	v_pk_mul_f32 v[48:49], v[46:47], s[44:45] op_sel_hi:[1,0]
	v_pk_mul_f32 v[50:51], v[44:45], s[44:45] op_sel_hi:[1,0]
	v_pk_mul_f32 v[44:45], v[38:39], s[44:45] op_sel_hi:[1,0]
	v_pk_mul_f32 v[46:47], v[36:37], s[44:45] op_sel_hi:[1,0]
	v_exp_f32_e32 v44, v44
	v_exp_f32_e32 v46, v46
	v_exp_f32_e32 v45, v45
	v_exp_f32_e32 v47, v47
	v_exp_f32_e32 v50, v50
	v_exp_f32_e32 v48, v48
	v_exp_f32_e32 v49, v49
	v_exp_f32_e32 v51, v51
	v_pk_add_f32 v[44:45], v[44:45], 1.0 op_sel_hi:[1,0]
	v_pk_add_f32 v[46:47], v[46:47], 1.0 op_sel_hi:[1,0]
	v_pk_add_f32 v[48:49], v[48:49], 1.0 op_sel_hi:[1,0]
	v_pk_add_f32 v[50:51], v[50:51], 1.0 op_sel_hi:[1,0]
	v_rcp_f32_e32 v46, v46
	v_rcp_f32_e32 v44, v44
	v_rcp_f32_e32 v45, v45
	v_rcp_f32_e32 v47, v47
	v_rcp_f32_e32 v50, v50
	v_rcp_f32_e32 v48, v48
	v_rcp_f32_e32 v49, v49
	v_rcp_f32_e32 v51, v51
	v_pk_mul_f32 v[34:35], v[34:35], v[132:133] op_sel_hi:[1,0]
	v_pk_mul_f32 v[32:33], v[32:33], v[132:133] op_sel_hi:[1,0]
	v_pk_mul_f32 v[34:35], v[38:39], v[34:35]
	v_pk_mul_f32 v[32:33], v[36:37], v[32:33]
	v_pk_mul_f32 v[36:37], v[34:35], v[44:45]
	v_pk_mul_f32 v[34:35], v[32:33], v[46:47]
	v_pk_mul_f32 v[42:43], v[42:43], v[48:49]
	v_pk_mul_f32 v[40:41], v[40:41], v[50:51]
	v_pk_mul_f32 v[30:31], v[30:31], v[130:131] op_sel_hi:[1,0]
	v_cvt_pk_bf16_f32 v32, v40, v41
	v_cvt_pk_bf16_f32 v33, v42, v43
	v_cvt_pk_bf16_f32 v34, v34, v35
	v_cvt_pk_bf16_f32 v35, v36, v37
	v_mad_i64_i32 v[36:37], s[4:5], v170, s35, v[112:113]
	v_lshl_add_u64 v[36:37], v[36:37], 0, v[114:115]
	v_pk_mul_f32 v[28:29], v[28:29], v[130:131] op_sel_hi:[1,0]
	v_pk_mul_f32 v[26:27], v[26:27], v[130:131] op_sel_hi:[1,0]
	v_pk_mul_f32 v[24:25], v[24:25], v[130:131] op_sel_hi:[1,0]
	v_pk_mul_f32 v[22:23], v[22:23], v[130:131] op_sel_hi:[1,0]
	v_pk_mul_f32 v[20:21], v[20:21], v[130:131] op_sel_hi:[1,0]
	global_store_dwordx4 v[36:37], v[32:35], off
	v_pk_mul_f32 v[24:25], v[28:29], v[24:25]
	v_pk_mul_f32 v[26:27], v[30:31], v[26:27]
	v_pk_mul_f32 v[32:33], v[30:31], s[44:45] op_sel_hi:[1,0]
	v_pk_mul_f32 v[34:35], v[28:29], s[44:45] op_sel_hi:[1,0]
	v_pk_mul_f32 v[28:29], v[22:23], s[44:45] op_sel_hi:[1,0]
	v_pk_mul_f32 v[30:31], v[20:21], s[44:45] op_sel_hi:[1,0]
	v_exp_f32_e32 v28, v28
	v_exp_f32_e32 v30, v30
	v_exp_f32_e32 v29, v29
	v_exp_f32_e32 v31, v31
	v_exp_f32_e32 v34, v34
	v_exp_f32_e32 v32, v32
	v_exp_f32_e32 v33, v33
	v_exp_f32_e32 v35, v35
	v_pk_add_f32 v[28:29], v[28:29], 1.0 op_sel_hi:[1,0]
	v_pk_add_f32 v[30:31], v[30:31], 1.0 op_sel_hi:[1,0]
	v_pk_add_f32 v[32:33], v[32:33], 1.0 op_sel_hi:[1,0]
	v_pk_add_f32 v[34:35], v[34:35], 1.0 op_sel_hi:[1,0]
	v_rcp_f32_e32 v30, v30
	v_rcp_f32_e32 v28, v28
	v_rcp_f32_e32 v29, v29
	v_rcp_f32_e32 v31, v31
	v_rcp_f32_e32 v34, v34
	v_rcp_f32_e32 v32, v32
	v_rcp_f32_e32 v33, v33
	v_rcp_f32_e32 v35, v35
	v_pk_mul_f32 v[18:19], v[18:19], v[130:131] op_sel_hi:[1,0]
	v_pk_mul_f32 v[16:17], v[16:17], v[130:131] op_sel_hi:[1,0]
	v_pk_mul_f32 v[18:19], v[22:23], v[18:19]
	v_pk_mul_f32 v[16:17], v[20:21], v[16:17]
	v_pk_mul_f32 v[20:21], v[18:19], v[28:29]
	v_pk_mul_f32 v[18:19], v[16:17], v[30:31]
	v_pk_mul_f32 v[26:27], v[26:27], v[32:33]
	v_pk_mul_f32 v[24:25], v[24:25], v[34:35]
	v_pk_mul_f32 v[14:15], v[14:15], v[128:129] op_sel_hi:[1,0]
	v_cvt_pk_bf16_f32 v16, v24, v25
	v_cvt_pk_bf16_f32 v17, v26, v27
	v_cvt_pk_bf16_f32 v18, v18, v19
	v_cvt_pk_bf16_f32 v19, v20, v21
	v_mad_i64_i32 v[20:21], s[4:5], v168, s35, v[112:113]
	v_lshl_add_u64 v[20:21], v[20:21], 0, v[114:115]
	v_pk_mul_f32 v[12:13], v[12:13], v[128:129] op_sel_hi:[1,0]
	v_pk_mul_f32 v[10:11], v[10:11], v[128:129] op_sel_hi:[1,0]
	v_pk_mul_f32 v[8:9], v[8:9], v[128:129] op_sel_hi:[1,0]
	v_pk_mul_f32 v[6:7], v[6:7], v[128:129] op_sel_hi:[1,0]
	v_pk_mul_f32 v[4:5], v[4:5], v[128:129] op_sel_hi:[1,0]
	global_store_dwordx4 v[20:21], v[16:19], off
	v_pk_mul_f32 v[8:9], v[12:13], v[8:9]
	v_pk_mul_f32 v[10:11], v[14:15], v[10:11]
	v_pk_mul_f32 v[16:17], v[14:15], s[44:45] op_sel_hi:[1,0]
	v_pk_mul_f32 v[18:19], v[12:13], s[44:45] op_sel_hi:[1,0]
	v_pk_mul_f32 v[12:13], v[6:7], s[44:45] op_sel_hi:[1,0]
	v_pk_mul_f32 v[14:15], v[4:5], s[44:45] op_sel_hi:[1,0]
	v_exp_f32_e32 v12, v12
	v_exp_f32_e32 v14, v14
	v_exp_f32_e32 v13, v13
	v_exp_f32_e32 v15, v15
	v_exp_f32_e32 v18, v18
	v_exp_f32_e32 v16, v16
	v_exp_f32_e32 v17, v17
	v_exp_f32_e32 v19, v19
	v_pk_add_f32 v[12:13], v[12:13], 1.0 op_sel_hi:[1,0]
	v_pk_add_f32 v[14:15], v[14:15], 1.0 op_sel_hi:[1,0]
	v_pk_add_f32 v[16:17], v[16:17], 1.0 op_sel_hi:[1,0]
	v_pk_add_f32 v[18:19], v[18:19], 1.0 op_sel_hi:[1,0]
	v_rcp_f32_e32 v14, v14
	v_rcp_f32_e32 v12, v12
	v_rcp_f32_e32 v13, v13
	v_rcp_f32_e32 v15, v15
	v_rcp_f32_e32 v18, v18
	v_rcp_f32_e32 v16, v16
	v_rcp_f32_e32 v17, v17
	v_rcp_f32_e32 v19, v19
	v_pk_mul_f32 v[2:3], v[2:3], v[128:129] op_sel_hi:[1,0]
	v_pk_mul_f32 v[0:1], v[0:1], v[128:129] op_sel_hi:[1,0]
	v_pk_mul_f32 v[2:3], v[6:7], v[2:3]
	v_pk_mul_f32 v[0:1], v[4:5], v[0:1]
	v_pk_mul_f32 v[4:5], v[2:3], v[12:13]
	v_pk_mul_f32 v[2:3], v[0:1], v[14:15]
	v_pk_mul_f32 v[10:11], v[10:11], v[16:17]
	v_pk_mul_f32 v[8:9], v[8:9], v[18:19]
	s_andn2_b64 vcc, exec, s[2:3]
	v_cvt_pk_bf16_f32 v0, v8, v9
	v_cvt_pk_bf16_f32 v1, v10, v11
	v_cvt_pk_bf16_f32 v2, v2, v3
	v_cvt_pk_bf16_f32 v3, v4, v5
	v_mad_i64_i32 v[4:5], s[4:5], v166, s35, v[112:113]
	v_lshl_add_u64 v[4:5], v[4:5], 0, v[114:115]
	s_mov_b32 s4, s16
	s_mov_b32 s5, s12
	s_mov_b64 s[6:7], s[18:19]
	global_store_dwordx4 v[4:5], v[0:3], off
	s_cbranch_vccnz .LBB0_1429
	s_waitcnt vmcnt(0)
	s_cmpk_gt_u32 s24, 0xff
	s_cbranch_scc1 .LBB0_1440
	s_barrier
